# stack: + gMLP transposed-write XOR swizzle (bank conflicts), tail-only priority raise for PV-active waves, prologue gain loads hoisted
# baseline (speedup 1.0000x reference)
; #define LAS __attribute__((address_space(3)))
; __device__ __forceinline__ void gmlp_unit(LAS unsigned char* lds, bf16_t* Z, const float* ln_g, const float* ln_b, const float* b_s, const u32x2 (&uu)[8], const f32x4 (&wreg)[8], const u32x4 (&raw)[4], int cidx, int g, int tid) {
;     constexpr int LSTR = 272;
;     LAS unsigned char* VT = lds; LAS unsigned char* WS = lds + 128 * LSTR;
;     const int row0 = cidx * 128;
;     {
;         const int j = tid >> 2, cq = (tid & 3) * 32;
;         float x[32];
.LBB0_421:
	s_andn2_b64 vcc, exec, s[0:1]
	s_cbranch_vccnz .LBB0_423
	s_load_dwordx2 s[6:7], s[92:93], 0x88
	s_load_dwordx8 s[8:15], s[92:93], 0x18
	v_readlane_b32 s22, v255, 18
	v_readlane_b32 s23, v255, 13
	v_lshrrev_b32_e32 v8, 2, v218
	v_and_b32_e32 v9, 3, v218
	v_and_b32_e32 v10, 15, v222
	v_lshrrev_b32_e32 v11, 4, v222
	v_lshrrev_b32_e32 v12, 6, v218
	v_lshl_add_u32 v13, v12, 4, v10
	s_lshl_b32 s16, s22, 1
	s_add_i32 s17, s16, 0x800
	v_mul_u32_u24_e32 v1, 0x3800, v8
	v_lshl_add_u32 v1, v9, 6, v1
	v_add_u32_e32 v1, s17, v1
	v_mul_u32_u24_e32 v2, 0x3800, v13
	v_lshl_add_u32 v2, v11, 3, v2
	v_add_u32_e32 v2, s16, v2
	v_mul_u32_u24_e32 v3, 0x2200, v9
	v_lshlrev_b32_e32 v14, 5, v9
	v_xor_b32_e32 v14, v8, v14
	v_lshl_add_u32 v3, v14, 1, v3
	v_mul_u32_u24_e32 v4, 0x110, v10
	v_lshl_add_u32 v4, v11, 4, v4
	v_mul_u32_u24_e32 v5, 0x110, v13
	v_lshl_add_u32 v5, v11, 4, v5
	v_add_u32_e32 v5, 0x11000, v5
	v_mul_u32_u24_e32 v6, 0x110, v8
	v_lshl_add_u32 v6, v9, 6, v6
	v_add_u32_e32 v6, 0x11000, v6
	v_lshlrev_b32_e32 v14, 7, v9
	v_lshlrev_b32_e32 v15, 2, v13
	v_lshl_add_u32 v12, v8, 9, v14
	v_lshlrev_b32_e32 v13, 5, v9
	v_sub_u32_e32 v13, v8, v13
	s_waitcnt lgkmcnt(0)
	s_add_u32 s6, s6, 0x11400000
	s_addc_u32 s7, s7, 0
	s_lshl_b32 s16, s74, 12
	s_lshl_b32 s17, s22, 2
	s_add_u32 s16, s16, s17
	s_add_u32 s8, s8, s16
	s_addc_u32 s9, s9, 0
	s_add_u32 s10, s10, s16
	s_addc_u32 s11, s11, 0
	s_add_u32 s14, s14, s16
	s_addc_u32 s15, s15, 0
	s_lshl_b32 s16, s74, 19
	s_lshl_b32 s17, s22, 9
	s_add_u32 s16, s16, s17
	s_add_u32 s12, s12, s16
	s_addc_u32 s13, s13, 0
	s_mul_i32 s18, s23, 0x3800
	s_add_u32 s20, s6, s18
	s_addc_u32 s21, s7, 0
	s_add_u32 s24, s20, 0x3800000
	s_addc_u32 s25, s21, 0
	s_add_u32 s26, s24, 0x3800000
	s_addc_u32 s27, s25, 0
	s_add_u32 s28, s26, 0x3800000
	s_addc_u32 s29, s27, 0
	global_load_dwordx4 v[160:163], v12, s[12:13]
	global_load_dwordx4 v[164:167], v12, s[12:13] offset:16
	global_load_dwordx4 v[168:171], v12, s[12:13] offset:32
	global_load_dwordx4 v[172:175], v12, s[12:13] offset:48
	global_load_dwordx4 v[176:179], v12, s[12:13] offset:64
	global_load_dwordx4 v[180:183], v12, s[12:13] offset:80
	global_load_dwordx4 v[184:187], v12, s[12:13] offset:96
	global_load_dwordx4 v[188:191], v12, s[12:13] offset:112
	global_load_dwordx4 v[16:19], v14, s[8:9]
	global_load_dwordx4 v[20:23], v14, s[8:9] offset:16
	global_load_dwordx4 v[24:27], v14, s[8:9] offset:32
	global_load_dwordx4 v[28:31], v14, s[8:9] offset:48
	global_load_dwordx4 v[32:35], v14, s[8:9] offset:64
	global_load_dwordx4 v[36:39], v14, s[8:9] offset:80
	global_load_dwordx4 v[40:43], v14, s[8:9] offset:96
	global_load_dwordx4 v[44:47], v14, s[8:9] offset:112
	global_load_dwordx4 v[48:51], v14, s[10:11]
	global_load_dwordx4 v[52:55], v14, s[10:11] offset:16
	global_load_dwordx4 v[56:59], v14, s[10:11] offset:32
	global_load_dwordx4 v[60:63], v14, s[10:11] offset:48
	global_load_dwordx4 v[64:67], v14, s[10:11] offset:64
	global_load_dwordx4 v[68:71], v14, s[10:11] offset:80
	global_load_dwordx4 v[72:75], v14, s[10:11] offset:96
	global_load_dwordx4 v[76:79], v14, s[10:11] offset:112
	global_load_dword v7, v15, s[14:15]
	global_load_dwordx4 v[96:99], v1, s[20:21]
	global_load_dwordx4 v[100:103], v1, s[20:21] offset:16
	global_load_dwordx4 v[104:107], v1, s[20:21] offset:32
	global_load_dwordx4 v[108:111], v1, s[20:21] offset:48
	global_load_dwordx2 v[112:113], v2, s[20:21]
	global_load_dwordx2 v[114:115], v2, s[20:21] offset:32
	global_load_dwordx2 v[116:117], v2, s[20:21] offset:64
	global_load_dwordx2 v[118:119], v2, s[20:21] offset:96
	global_load_dwordx2 v[120:121], v2, s[20:21] offset:128
	global_load_dwordx2 v[122:123], v2, s[20:21] offset:160
	global_load_dwordx2 v[124:125], v2, s[20:21] offset:192
	global_load_dwordx2 v[126:127], v2, s[20:21] offset:224
	global_load_dwordx4 v[128:131], v1, s[24:25]
	global_load_dwordx4 v[132:135], v1, s[24:25] offset:16
	global_load_dwordx4 v[136:139], v1, s[24:25] offset:32
	global_load_dwordx4 v[140:143], v1, s[24:25] offset:48
	global_load_dwordx2 v[144:145], v2, s[24:25]
	global_load_dwordx2 v[146:147], v2, s[24:25] offset:32
	global_load_dwordx2 v[148:149], v2, s[24:25] offset:64
	global_load_dwordx2 v[150:151], v2, s[24:25] offset:96
	global_load_dwordx2 v[152:153], v2, s[24:25] offset:128
	global_load_dwordx2 v[154:155], v2, s[24:25] offset:160
	global_load_dwordx2 v[156:157], v2, s[24:25] offset:192
	global_load_dwordx2 v[158:159], v2, s[24:25] offset:224
	s_waitcnt vmcnt(41)
; #define LAS __attribute__((address_space(3)))
; __device__ __forceinline__ unsigned pk2(float lo, float hi) { return pg8::cvt_pk_bf16(lo, hi); }
; __device__ __forceinline__ void gmlp_unit(LAS unsigned char* lds, bf16_t* Z, const float* ln_g, const float* ln_b, const float* b_s, const u32x2 (&uu)[8], const f32x4 (&wreg)[8], const u32x4 (&raw)[4], int cidx, int g, int tid) {
;     ...
;         const int j = tid >> 2, cq = (tid & 3) * 32;
;         float x[32];
; #pragma unroll
;         for (int q = 0; q < 4; ++q)
; #pragma unroll
;             for (int e = 0; e < 4; ++e) { x[8 * q + 2 * e] = bf_lo(raw[q][e]); x[8 * q + 2 * e + 1] = bf_hi(raw[q][e]); }
;         float s = 0.f;
; #pragma unroll
;         for (int c = 0; c < 32; ++c) s += x[c];
;         s += __shfl_xor(s, 1); s += __shfl_xor(s, 2);
;         const float mean = s * (1.f / 128.f); float q2 = 0.f;
; #pragma unroll
;     ...
;         const int i = tid >> 2, jq = (tid & 3) * 32;
; #pragma unroll
;         for (int q = 0; q < 4; ++q) { f32x4 a = wreg[2 * q], b = wreg[2 * q + 1];
;             const int j0 = jq + 8 * q;
; #pragma unroll
;             for (int e = 0; e < 4; ++e) { if (j0 + e > i) a[e] = 0.f; if (j0 + 4 + e > i) b[e] = 0.f; }
;             u32x4 w; w.x = pk2(a[0], a[1]); w.y = pk2(a[2], a[3]); w.z = pk2(b[0], b[1]); w.w = pk2(b[2], b[3]);
;             *(LAS u32x4*)(WS + i * LSTR + j0 * 2) = w; }
	v_cmp_gt_i32_e64 s[30:31], 0, v13
	v_cmp_gt_i32_e64 s[34:35], 1, v13
	v_cmp_gt_i32_e64 s[36:37], 2, v13
	v_cmp_gt_i32_e64 s[38:39], 3, v13
	v_cmp_gt_i32_e64 s[40:41], 4, v13
	v_cmp_gt_i32_e64 s[42:43], 5, v13
	v_cmp_gt_i32_e64 s[44:45], 6, v13
	v_cmp_gt_i32_e64 s[46:47], 7, v13
	v_cmp_gt_i32_e64 s[48:49], 8, v13
	v_cmp_gt_i32_e64 s[50:51], 9, v13
	v_cmp_gt_i32_e64 s[52:53], 10, v13
	v_cmp_gt_i32_e64 s[54:55], 11, v13
	v_cmp_gt_i32_e64 s[56:57], 12, v13
	v_cmp_gt_i32_e64 s[58:59], 13, v13
	v_cmp_gt_i32_e64 s[60:61], 14, v13
	v_cmp_gt_i32_e64 s[62:63], 15, v13
	v_cndmask_b32_e64 v160, v160, 0, s[30:31]
	v_cndmask_b32_e64 v161, v161, 0, s[34:35]
	v_cndmask_b32_e64 v162, v162, 0, s[36:37]
	v_cndmask_b32_e64 v163, v163, 0, s[38:39]
	v_cndmask_b32_e64 v164, v164, 0, s[40:41]
	v_cndmask_b32_e64 v165, v165, 0, s[42:43]
	v_cndmask_b32_e64 v166, v166, 0, s[44:45]
	v_cndmask_b32_e64 v167, v167, 0, s[46:47]
	v_cndmask_b32_e64 v168, v168, 0, s[48:49]
	v_cndmask_b32_e64 v169, v169, 0, s[50:51]
	v_cndmask_b32_e64 v170, v170, 0, s[52:53]
	v_cndmask_b32_e64 v171, v171, 0, s[54:55]
	v_cndmask_b32_e64 v172, v172, 0, s[56:57]
	v_cndmask_b32_e64 v173, v173, 0, s[58:59]
	v_cndmask_b32_e64 v174, v174, 0, s[60:61]
	v_cndmask_b32_e64 v175, v175, 0, s[62:63]
	v_cmp_gt_i32_e64 s[30:31], 16, v13
	v_cmp_gt_i32_e64 s[34:35], 17, v13
	v_cmp_gt_i32_e64 s[36:37], 18, v13
	v_cmp_gt_i32_e64 s[38:39], 19, v13
	v_cmp_gt_i32_e64 s[40:41], 20, v13
	v_cmp_gt_i32_e64 s[42:43], 21, v13
	v_cmp_gt_i32_e64 s[44:45], 22, v13
	v_cmp_gt_i32_e64 s[46:47], 23, v13
	v_cmp_gt_i32_e64 s[48:49], 24, v13
	v_cmp_gt_i32_e64 s[50:51], 25, v13
	v_cmp_gt_i32_e64 s[52:53], 26, v13
	v_cmp_gt_i32_e64 s[54:55], 27, v13
	v_cmp_gt_i32_e64 s[56:57], 28, v13
	v_cmp_gt_i32_e64 s[58:59], 29, v13
	v_cmp_gt_i32_e64 s[60:61], 30, v13
	v_cmp_gt_i32_e64 s[62:63], 31, v13
	v_cndmask_b32_e64 v176, v176, 0, s[30:31]
	v_cndmask_b32_e64 v177, v177, 0, s[34:35]
	v_cndmask_b32_e64 v178, v178, 0, s[36:37]
	v_cndmask_b32_e64 v179, v179, 0, s[38:39]
	v_cndmask_b32_e64 v180, v180, 0, s[40:41]
	v_cndmask_b32_e64 v181, v181, 0, s[42:43]
	v_cndmask_b32_e64 v182, v182, 0, s[44:45]
	v_cndmask_b32_e64 v183, v183, 0, s[46:47]
	v_cndmask_b32_e64 v184, v184, 0, s[48:49]
	v_cndmask_b32_e64 v185, v185, 0, s[50:51]
	v_cndmask_b32_e64 v186, v186, 0, s[52:53]
	v_cndmask_b32_e64 v187, v187, 0, s[54:55]
	v_cndmask_b32_e64 v188, v188, 0, s[56:57]
	v_cndmask_b32_e64 v189, v189, 0, s[58:59]
	v_cndmask_b32_e64 v190, v190, 0, s[60:61]
	v_cndmask_b32_e64 v191, v191, 0, s[62:63]
	v_cvt_pk_bf16_f32 v160, v160, v161
	v_cvt_pk_bf16_f32 v161, v162, v163
	v_cvt_pk_bf16_f32 v162, v164, v165
	v_cvt_pk_bf16_f32 v163, v166, v167
	v_cvt_pk_bf16_f32 v164, v168, v169
	v_cvt_pk_bf16_f32 v165, v170, v171
	v_cvt_pk_bf16_f32 v166, v172, v173
	v_cvt_pk_bf16_f32 v167, v174, v175
	v_cvt_pk_bf16_f32 v168, v176, v177
	v_cvt_pk_bf16_f32 v169, v178, v179
	v_cvt_pk_bf16_f32 v170, v180, v181
	v_cvt_pk_bf16_f32 v171, v182, v183
	v_cvt_pk_bf16_f32 v172, v184, v185
	v_cvt_pk_bf16_f32 v173, v186, v187
	v_cvt_pk_bf16_f32 v174, v188, v189
	v_cvt_pk_bf16_f32 v175, v190, v191
	ds_write_b128 v6, v[160:163]
	ds_write_b128 v6, v[164:167] offset:16
	ds_write_b128 v6, v[168:171] offset:32
	ds_write_b128 v6, v[172:175] offset:48
	s_waitcnt vmcnt(20)
	v_lshlrev_b32_e32 v160, 16, v96
	v_and_b32_e32 v161, 0xffff0000, v96
	v_lshlrev_b32_e32 v162, 16, v97
	v_and_b32_e32 v163, 0xffff0000, v97
	v_lshlrev_b32_e32 v164, 16, v98
	v_and_b32_e32 v165, 0xffff0000, v98
	v_lshlrev_b32_e32 v166, 16, v99
	v_and_b32_e32 v167, 0xffff0000, v99
	v_lshlrev_b32_e32 v168, 16, v100
	v_and_b32_e32 v169, 0xffff0000, v100
	v_lshlrev_b32_e32 v170, 16, v101
	v_and_b32_e32 v171, 0xffff0000, v101
	v_lshlrev_b32_e32 v172, 16, v102
	v_and_b32_e32 v173, 0xffff0000, v102
	v_lshlrev_b32_e32 v174, 16, v103
	v_and_b32_e32 v175, 0xffff0000, v103
	v_lshlrev_b32_e32 v176, 16, v104
	v_and_b32_e32 v177, 0xffff0000, v104
	v_lshlrev_b32_e32 v178, 16, v105
	v_and_b32_e32 v179, 0xffff0000, v105
	v_lshlrev_b32_e32 v180, 16, v106
	v_and_b32_e32 v181, 0xffff0000, v106
	v_lshlrev_b32_e32 v182, 16, v107
	v_and_b32_e32 v183, 0xffff0000, v107
	v_lshlrev_b32_e32 v184, 16, v108
	v_and_b32_e32 v185, 0xffff0000, v108
	v_lshlrev_b32_e32 v186, 16, v109
	v_and_b32_e32 v187, 0xffff0000, v109
	v_lshlrev_b32_e32 v188, 16, v110
	v_and_b32_e32 v189, 0xffff0000, v110
	v_lshlrev_b32_e32 v190, 16, v111
	v_and_b32_e32 v191, 0xffff0000, v111
	v_add_f32_e32 v8, v160, v164
	v_add_f32_e32 v9, v161, v165
	v_add_f32_e32 v10, v162, v166
	v_add_f32_e32 v11, v163, v167
	v_add_f32_e32 v8, v8, v168
	v_add_f32_e32 v9, v9, v169
	v_add_f32_e32 v10, v10, v170
	v_add_f32_e32 v11, v11, v171
	v_add_f32_e32 v8, v8, v172
	v_add_f32_e32 v9, v9, v173
	v_add_f32_e32 v10, v10, v174
	v_add_f32_e32 v11, v11, v175
	v_add_f32_e32 v8, v8, v176
	v_add_f32_e32 v9, v9, v177
	v_add_f32_e32 v10, v10, v178
	v_add_f32_e32 v11, v11, v179
	v_add_f32_e32 v8, v8, v180
	v_add_f32_e32 v9, v9, v181
	v_add_f32_e32 v10, v10, v182
	v_add_f32_e32 v11, v11, v183
	v_add_f32_e32 v8, v8, v184
	v_add_f32_e32 v9, v9, v185
	v_add_f32_e32 v10, v10, v186
	v_add_f32_e32 v11, v11, v187
	v_add_f32_e32 v8, v8, v188
	v_add_f32_e32 v9, v9, v189
	v_add_f32_e32 v10, v10, v190
	v_add_f32_e32 v11, v11, v191
	v_add_f32_e32 v8, v8, v9
	v_add_f32_e32 v10, v10, v11
	v_add_f32_e32 v8, v8, v10
	s_nop 1
	v_add_f32_dpp v8, v8, v8 quad_perm:[1,0,3,2] row_mask:0xf bank_mask:0xf
	s_nop 1
	v_add_f32_dpp v8, v8, v8 quad_perm:[2,3,0,1] row_mask:0xf bank_mask:0xf
	v_mul_f32_e32 v8, 0xbc000000, v8
	v_add_f32_e32 v160, v160, v8
	v_add_f32_e32 v161, v161, v8
	v_add_f32_e32 v162, v162, v8
	v_add_f32_e32 v163, v163, v8
; #define LAS __attribute__((address_space(3)))
; __device__ __forceinline__ unsigned f2bf(float f) { unsigned u = __builtin_bit_cast(unsigned, f); return (u + 0x7fffu + ((u >> 16) & 1u)) >> 16; }
; __device__ __forceinline__ void gmlp_unit(LAS unsigned char* lds, bf16_t* Z, const float* ln_g, const float* ln_b, const float* b_s, const u32x2 (&uu)[8], const f32x4 (&wreg)[8], const u32x4 (&raw)[4], int cidx, int g, int tid) {
;     ...
;         const float mean = s * (1.f / 128.f); float q2 = 0.f;
; #pragma unroll
;         for (int c = 0; c < 32; ++c) { x[c] -= mean; q2 += x[c] * x[c]; }
;         q2 += __shfl_xor(q2, 1); q2 += __shfl_xor(q2, 2);
;         const float rstd = __builtin_amdgcn_rsqf(q2 * (1.f / 128.f) + EPS);
;         const float* gp = ln_g + g * 128 + cq; const float* bp = ln_b + g * 128 + cq;
; #pragma unroll
;         for (int c4 = 0; c4 < 8; ++c4) { const f32x4 gg = *(const f32x4*)(gp + 4 * c4), bb = *(const f32x4*)(bp + 4 * c4);
; #pragma unroll
;             for (int e = 0; e < 4; ++e) { const int c = 4 * c4 + e; const float y = x[c] * rstd * gg[e] + bb[e];
;                 *(LAS unsigned short*)(VT + (cq + c) * LSTR + j * 2) = (unsigned short)f2bf(y); } }
	v_add_f32_e32 v164, v164, v8
	v_add_f32_e32 v165, v165, v8
	v_add_f32_e32 v166, v166, v8
	v_add_f32_e32 v167, v167, v8
	v_add_f32_e32 v168, v168, v8
	v_add_f32_e32 v169, v169, v8
	v_add_f32_e32 v170, v170, v8
	v_add_f32_e32 v171, v171, v8
	v_add_f32_e32 v172, v172, v8
	v_add_f32_e32 v173, v173, v8
	v_add_f32_e32 v174, v174, v8
	v_add_f32_e32 v175, v175, v8
	v_add_f32_e32 v176, v176, v8
	v_add_f32_e32 v177, v177, v8
	v_add_f32_e32 v178, v178, v8
	v_add_f32_e32 v179, v179, v8
	v_add_f32_e32 v180, v180, v8
	v_add_f32_e32 v181, v181, v8
	v_add_f32_e32 v182, v182, v8
	v_add_f32_e32 v183, v183, v8
	v_add_f32_e32 v184, v184, v8
	v_add_f32_e32 v185, v185, v8
	v_add_f32_e32 v186, v186, v8
	v_add_f32_e32 v187, v187, v8
	v_add_f32_e32 v188, v188, v8
	v_add_f32_e32 v189, v189, v8
	v_add_f32_e32 v190, v190, v8
	v_add_f32_e32 v191, v191, v8
	v_mul_f32_e32 v8, v160, v160
	v_mul_f32_e32 v9, v161, v161
	v_mul_f32_e32 v10, v162, v162
	v_mul_f32_e32 v11, v163, v163
	v_fmac_f32_e32 v8, v164, v164
	v_fmac_f32_e32 v9, v165, v165
	v_fmac_f32_e32 v10, v166, v166
	v_fmac_f32_e32 v11, v167, v167
	v_fmac_f32_e32 v8, v168, v168
	v_fmac_f32_e32 v9, v169, v169
	v_fmac_f32_e32 v10, v170, v170
	v_fmac_f32_e32 v11, v171, v171
	v_fmac_f32_e32 v8, v172, v172
	v_fmac_f32_e32 v9, v173, v173
	v_fmac_f32_e32 v10, v174, v174
	v_fmac_f32_e32 v11, v175, v175
	v_fmac_f32_e32 v8, v176, v176
	v_fmac_f32_e32 v9, v177, v177
	v_fmac_f32_e32 v10, v178, v178
	v_fmac_f32_e32 v11, v179, v179
	v_fmac_f32_e32 v8, v180, v180
	v_fmac_f32_e32 v9, v181, v181
	v_fmac_f32_e32 v10, v182, v182
	v_fmac_f32_e32 v11, v183, v183
	v_fmac_f32_e32 v8, v184, v184
	v_fmac_f32_e32 v9, v185, v185
	v_fmac_f32_e32 v10, v186, v186
	v_fmac_f32_e32 v11, v187, v187
	v_fmac_f32_e32 v8, v188, v188
	v_fmac_f32_e32 v9, v189, v189
	v_fmac_f32_e32 v10, v190, v190
	v_fmac_f32_e32 v11, v191, v191
	v_add_f32_e32 v8, v8, v9
	v_add_f32_e32 v10, v10, v11
	v_add_f32_e32 v8, v8, v10
	s_nop 1
	v_add_f32_dpp v8, v8, v8 quad_perm:[1,0,3,2] row_mask:0xf bank_mask:0xf
	s_nop 1
	v_add_f32_dpp v8, v8, v8 quad_perm:[2,3,0,1] row_mask:0xf bank_mask:0xf
	v_fmamk_f32 v8, v8, 0x3c000000, v219
	v_rsq_f32_e32 v8, v8
	s_nop 0
	v_mul_f32_e32 v160, v160, v8
	v_fma_f32 v160, v16, v160, v48
	v_bfe_u32 v9, v160, 16, 1
	v_add3_u32 v160, v160, v9, s81
	ds_write_b16_d16_hi v3, v160
	v_mul_f32_e32 v161, v161, v8
	v_fma_f32 v161, v17, v161, v49
	v_bfe_u32 v10, v161, 16, 1
	v_add3_u32 v161, v161, v10, s81
	ds_write_b16_d16_hi v3, v161 offset:272
	v_mul_f32_e32 v162, v162, v8
	v_fma_f32 v162, v18, v162, v50
	v_bfe_u32 v9, v162, 16, 1
	v_add3_u32 v162, v162, v9, s81
	ds_write_b16_d16_hi v3, v162 offset:544
	v_mul_f32_e32 v163, v163, v8
	v_fma_f32 v163, v19, v163, v51
	v_bfe_u32 v10, v163, 16, 1
	v_add3_u32 v163, v163, v10, s81
	ds_write_b16_d16_hi v3, v163 offset:816
	v_mul_f32_e32 v164, v164, v8
	v_fma_f32 v164, v20, v164, v52
	v_bfe_u32 v9, v164, 16, 1
	v_add3_u32 v164, v164, v9, s81
	ds_write_b16_d16_hi v3, v164 offset:1088
	v_mul_f32_e32 v165, v165, v8
	v_fma_f32 v165, v21, v165, v53
	v_bfe_u32 v10, v165, 16, 1
	v_add3_u32 v165, v165, v10, s81
	ds_write_b16_d16_hi v3, v165 offset:1360
	v_mul_f32_e32 v166, v166, v8
	v_fma_f32 v166, v22, v166, v54
	v_bfe_u32 v9, v166, 16, 1
	v_add3_u32 v166, v166, v9, s81
	ds_write_b16_d16_hi v3, v166 offset:1632
	v_mul_f32_e32 v167, v167, v8
	v_fma_f32 v167, v23, v167, v55
	v_bfe_u32 v10, v167, 16, 1
	v_add3_u32 v167, v167, v10, s81
	ds_write_b16_d16_hi v3, v167 offset:1904
	v_mul_f32_e32 v168, v168, v8
	v_fma_f32 v168, v24, v168, v56
	v_bfe_u32 v9, v168, 16, 1
	v_add3_u32 v168, v168, v9, s81
	ds_write_b16_d16_hi v3, v168 offset:2176
	v_mul_f32_e32 v169, v169, v8
	v_fma_f32 v169, v25, v169, v57
	v_bfe_u32 v10, v169, 16, 1
	v_add3_u32 v169, v169, v10, s81
	ds_write_b16_d16_hi v3, v169 offset:2448
	v_mul_f32_e32 v170, v170, v8
	v_fma_f32 v170, v26, v170, v58
	v_bfe_u32 v9, v170, 16, 1
	v_add3_u32 v170, v170, v9, s81
	ds_write_b16_d16_hi v3, v170 offset:2720
	v_mul_f32_e32 v171, v171, v8
	v_fma_f32 v171, v27, v171, v59
	v_bfe_u32 v10, v171, 16, 1
	v_add3_u32 v171, v171, v10, s81
	ds_write_b16_d16_hi v3, v171 offset:2992
	v_mul_f32_e32 v172, v172, v8
	v_fma_f32 v172, v28, v172, v60
	v_bfe_u32 v9, v172, 16, 1
	v_add3_u32 v172, v172, v9, s81
	ds_write_b16_d16_hi v3, v172 offset:3264
	v_mul_f32_e32 v173, v173, v8
	v_fma_f32 v173, v29, v173, v61
	v_bfe_u32 v10, v173, 16, 1
	v_add3_u32 v173, v173, v10, s81
	ds_write_b16_d16_hi v3, v173 offset:3536
	v_mul_f32_e32 v174, v174, v8
	v_fma_f32 v174, v30, v174, v62
	v_bfe_u32 v9, v174, 16, 1
	v_add3_u32 v174, v174, v9, s81
	ds_write_b16_d16_hi v3, v174 offset:3808
	v_mul_f32_e32 v175, v175, v8
	v_fma_f32 v175, v31, v175, v63
	v_bfe_u32 v10, v175, 16, 1
	v_add3_u32 v175, v175, v10, s81
	ds_write_b16_d16_hi v3, v175 offset:4080
	v_mul_f32_e32 v176, v176, v8
	v_fma_f32 v176, v32, v176, v64
	v_bfe_u32 v9, v176, 16, 1
	v_add3_u32 v176, v176, v9, s81
	ds_write_b16_d16_hi v3, v176 offset:4352
	v_mul_f32_e32 v177, v177, v8
	v_fma_f32 v177, v33, v177, v65
	v_bfe_u32 v10, v177, 16, 1
	v_add3_u32 v177, v177, v10, s81
	ds_write_b16_d16_hi v3, v177 offset:4624
	v_mul_f32_e32 v178, v178, v8
	v_fma_f32 v178, v34, v178, v66
	v_bfe_u32 v9, v178, 16, 1
	v_add3_u32 v178, v178, v9, s81
	ds_write_b16_d16_hi v3, v178 offset:4896
	v_mul_f32_e32 v179, v179, v8
	v_fma_f32 v179, v35, v179, v67
	v_bfe_u32 v10, v179, 16, 1
	v_add3_u32 v179, v179, v10, s81
	ds_write_b16_d16_hi v3, v179 offset:5168
	v_mul_f32_e32 v180, v180, v8
	v_fma_f32 v180, v36, v180, v68
	v_bfe_u32 v9, v180, 16, 1
	v_add3_u32 v180, v180, v9, s81
	ds_write_b16_d16_hi v3, v180 offset:5440
	v_mul_f32_e32 v181, v181, v8
	v_fma_f32 v181, v37, v181, v69
; #define LAS __attribute__((address_space(3)))
; __device__ __forceinline__ unsigned f2bf(float f) { unsigned u = __builtin_bit_cast(unsigned, f); return (u + 0x7fffu + ((u >> 16) & 1u)) >> 16; }
; __device__ __forceinline__ unsigned pk2(float lo, float hi) { return pg8::cvt_pk_bf16(lo, hi); }
; __device__ __forceinline__ void gmlp_unit(LAS unsigned char* lds, bf16_t* Z, const float* ln_g, const float* ln_b, const float* b_s, const u32x2 (&uu)[8], const f32x4 (&wreg)[8], const u32x4 (&raw)[4], int cidx, int g, int tid) {
;     ...
;             for (int e = 0; e < 4; ++e) { const int c = 4 * c4 + e; const float y = x[c] * rstd * gg[e] + bb[e];
;                 *(LAS unsigned short*)(VT + (cq + c) * LSTR + j * 2) = (unsigned short)f2bf(y); } }
;     }
;     {
;         const int i = tid >> 2, jq = (tid & 3) * 32;
; #pragma unroll
;         for (int q = 0; q < 4; ++q) { f32x4 a = wreg[2 * q], b = wreg[2 * q + 1];
;             const int j0 = jq + 8 * q;
; #pragma unroll
;             for (int e = 0; e < 4; ++e) { if (j0 + e > i) a[e] = 0.f; if (j0 + 4 + e > i) b[e] = 0.f; }
;             u32x4 w; w.x = pk2(a[0], a[1]); w.y = pk2(a[2], a[3]); w.z = pk2(b[0], b[1]); w.w = pk2(b[2], b[3]);
;             *(LAS u32x4*)(WS + i * LSTR + j0 * 2) = w; }
;     }
;     __syncthreads();
;     const int wv = tid >> 6, lane = tid & 63, fr = lane & 15, fq = lane >> 4;
;     f32x4 acc[8];
; #pragma unroll
;     for (int ct = 0; ct < 8; ++ct) acc[ct] = (f32x4){0.f, 0.f, 0.f, 0.f};
; #pragma unroll
;     for (int ks = 0; ks < 4; ++ks) {
;         const bf16x8 bw = *(const LAS bf16x8*)(WS + (wv * 16 + fr) * LSTR + (ks * 32 + fq * 8) * 2);
; #pragma unroll
;         for (int ct = 0; ct < 8; ++ct) { const bf16x8 av = *(const LAS bf16x8*)(VT + (ct * 16 + fr) * LSTR + (ks * 32 + fq * 8) * 2);
;             acc[ct] = __builtin_amdgcn_mfma_f32_16x16x32_bf16(av, bw, acc[ct], 0, 0, 0); }
	v_bfe_u32 v10, v181, 16, 1
	v_add3_u32 v181, v181, v10, s81
	ds_write_b16_d16_hi v3, v181 offset:5712
	v_mul_f32_e32 v182, v182, v8
	v_fma_f32 v182, v38, v182, v70
	v_bfe_u32 v9, v182, 16, 1
	v_add3_u32 v182, v182, v9, s81
	ds_write_b16_d16_hi v3, v182 offset:5984
	v_mul_f32_e32 v183, v183, v8
	v_fma_f32 v183, v39, v183, v71
	v_bfe_u32 v10, v183, 16, 1
	v_add3_u32 v183, v183, v10, s81
	ds_write_b16_d16_hi v3, v183 offset:6256
	v_mul_f32_e32 v184, v184, v8
	v_fma_f32 v184, v40, v184, v72
	v_bfe_u32 v9, v184, 16, 1
	v_add3_u32 v184, v184, v9, s81
	ds_write_b16_d16_hi v3, v184 offset:6528
	v_mul_f32_e32 v185, v185, v8
	v_fma_f32 v185, v41, v185, v73
	v_bfe_u32 v10, v185, 16, 1
	v_add3_u32 v185, v185, v10, s81
	ds_write_b16_d16_hi v3, v185 offset:6800
	v_mul_f32_e32 v186, v186, v8
	v_fma_f32 v186, v42, v186, v74
	v_bfe_u32 v9, v186, 16, 1
	v_add3_u32 v186, v186, v9, s81
	ds_write_b16_d16_hi v3, v186 offset:7072
	v_mul_f32_e32 v187, v187, v8
	v_fma_f32 v187, v43, v187, v75
	v_bfe_u32 v10, v187, 16, 1
	v_add3_u32 v187, v187, v10, s81
	ds_write_b16_d16_hi v3, v187 offset:7344
	v_mul_f32_e32 v188, v188, v8
	v_fma_f32 v188, v44, v188, v76
	v_bfe_u32 v9, v188, 16, 1
	v_add3_u32 v188, v188, v9, s81
	ds_write_b16_d16_hi v3, v188 offset:7616
	v_mul_f32_e32 v189, v189, v8
	v_fma_f32 v189, v45, v189, v77
	v_bfe_u32 v10, v189, 16, 1
	v_add3_u32 v189, v189, v10, s81
	ds_write_b16_d16_hi v3, v189 offset:7888
	v_mul_f32_e32 v190, v190, v8
	v_fma_f32 v190, v46, v190, v78
	v_bfe_u32 v9, v190, 16, 1
	v_add3_u32 v190, v190, v9, s81
	ds_write_b16_d16_hi v3, v190 offset:8160
	v_mul_f32_e32 v191, v191, v8
	v_fma_f32 v191, v47, v191, v79
	v_bfe_u32 v10, v191, 16, 1
	v_add3_u32 v191, v191, v10, s81
	ds_write_b16_d16_hi v3, v191 offset:8432
	s_waitcnt lgkmcnt(0)
	s_barrier
	ds_read_b128 v[80:83], v5
	ds_read_b128 v[84:87], v5 offset:64
	ds_read_b128 v[88:91], v5 offset:128
	ds_read_b128 v[92:95], v5 offset:192
	ds_read_b128 v[200:203], v4
	ds_read_b128 v[204:207], v4 offset:4352
	ds_read_b128 v[208:211], v4 offset:8768
	ds_read_b128 v[212:215], v4 offset:13120
	ds_read_b128 v[224:227], v4 offset:17536
	ds_read_b128 v[228:231], v4 offset:21888
	ds_read_b128 v[232:235], v4 offset:26304
	ds_read_b128 v[236:239], v4 offset:30656
	s_waitcnt lgkmcnt(7)
	v_mfma_f32_16x16x32_bf16 v[160:163], v[200:203], v[80:83], 0
	ds_read_b128 v[200:203], v4 offset:64
	s_waitcnt lgkmcnt(7)
	v_mfma_f32_16x16x32_bf16 v[164:167], v[204:207], v[80:83], 0
	ds_read_b128 v[204:207], v4 offset:4416
	s_waitcnt lgkmcnt(7)
	v_mfma_f32_16x16x32_bf16 v[168:171], v[208:211], v[80:83], 0
	ds_read_b128 v[208:211], v4 offset:8704
	s_waitcnt lgkmcnt(7)
	v_mfma_f32_16x16x32_bf16 v[172:175], v[212:215], v[80:83], 0
	ds_read_b128 v[212:215], v4 offset:13056
	s_waitcnt lgkmcnt(7)
	v_mfma_f32_16x16x32_bf16 v[176:179], v[224:227], v[80:83], 0
	ds_read_b128 v[224:227], v4 offset:17600
	s_waitcnt lgkmcnt(7)
	v_mfma_f32_16x16x32_bf16 v[180:183], v[228:231], v[80:83], 0
	ds_read_b128 v[228:231], v4 offset:21952
	s_waitcnt lgkmcnt(7)
	v_mfma_f32_16x16x32_bf16 v[184:187], v[232:235], v[80:83], 0
	ds_read_b128 v[232:235], v4 offset:26240
	s_waitcnt lgkmcnt(7)
	v_mfma_f32_16x16x32_bf16 v[188:191], v[236:239], v[80:83], 0
	ds_read_b128 v[236:239], v4 offset:30592
	s_waitcnt lgkmcnt(7)
	v_mfma_f32_16x16x32_bf16 v[160:163], v[200:203], v[84:87], v[160:163]
	ds_read_b128 v[200:203], v4 offset:128
	s_waitcnt lgkmcnt(7)
	v_mfma_f32_16x16x32_bf16 v[164:167], v[204:207], v[84:87], v[164:167]
	ds_read_b128 v[204:207], v4 offset:4480
	s_waitcnt lgkmcnt(7)
	v_mfma_f32_16x16x32_bf16 v[168:171], v[208:211], v[84:87], v[168:171]
	ds_read_b128 v[208:211], v4 offset:8896
	s_waitcnt lgkmcnt(7)
	v_mfma_f32_16x16x32_bf16 v[172:175], v[212:215], v[84:87], v[172:175]
	ds_read_b128 v[212:215], v4 offset:13248
	s_waitcnt lgkmcnt(7)
	v_mfma_f32_16x16x32_bf16 v[176:179], v[224:227], v[84:87], v[176:179]
	ds_read_b128 v[224:227], v4 offset:17408
	s_waitcnt lgkmcnt(7)
	v_mfma_f32_16x16x32_bf16 v[180:183], v[228:231], v[84:87], v[180:183]
	ds_read_b128 v[228:231], v4 offset:21760
	s_waitcnt lgkmcnt(7)
	v_mfma_f32_16x16x32_bf16 v[184:187], v[232:235], v[84:87], v[184:187]
	ds_read_b128 v[232:235], v4 offset:26176
	s_waitcnt lgkmcnt(7)
	v_mfma_f32_16x16x32_bf16 v[188:191], v[236:239], v[84:87], v[188:191]
	ds_read_b128 v[236:239], v4 offset:30528
	s_waitcnt lgkmcnt(7)
	v_mfma_f32_16x16x32_bf16 v[160:163], v[200:203], v[88:91], v[160:163]
	ds_read_b128 v[200:203], v4 offset:192
	s_waitcnt lgkmcnt(7)
	v_mfma_f32_16x16x32_bf16 v[164:167], v[204:207], v[88:91], v[164:167]
	ds_read_b128 v[204:207], v4 offset:4544
	s_waitcnt lgkmcnt(7)
	v_mfma_f32_16x16x32_bf16 v[168:171], v[208:211], v[88:91], v[168:171]
	ds_read_b128 v[208:211], v4 offset:8832
	s_waitcnt lgkmcnt(7)
	v_mfma_f32_16x16x32_bf16 v[172:175], v[212:215], v[88:91], v[172:175]
	ds_read_b128 v[212:215], v4 offset:13184
	s_waitcnt lgkmcnt(7)
	v_mfma_f32_16x16x32_bf16 v[176:179], v[224:227], v[88:91], v[176:179]
	ds_read_b128 v[224:227], v4 offset:17472
	s_waitcnt lgkmcnt(7)
	v_mfma_f32_16x16x32_bf16 v[180:183], v[228:231], v[88:91], v[180:183]
	ds_read_b128 v[228:231], v4 offset:21824
	s_waitcnt lgkmcnt(7)
	v_mfma_f32_16x16x32_bf16 v[184:187], v[232:235], v[88:91], v[184:187]
	ds_read_b128 v[232:235], v4 offset:26112
	s_waitcnt lgkmcnt(7)
	v_mfma_f32_16x16x32_bf16 v[188:191], v[236:239], v[88:91], v[188:191]
	ds_read_b128 v[236:239], v4 offset:30464
	s_waitcnt lgkmcnt(7)
	v_mfma_f32_16x16x32_bf16 v[160:163], v[200:203], v[92:95], v[160:163]
	s_waitcnt lgkmcnt(6)
	v_mfma_f32_16x16x32_bf16 v[164:167], v[204:207], v[92:95], v[164:167]
	s_waitcnt lgkmcnt(5)
; __device__ __forceinline__ unsigned pk2(float lo, float hi) { return pg8::cvt_pk_bf16(lo, hi); }
; __device__ __forceinline__ void gmlp_unit(LAS unsigned char* lds, bf16_t* Z, const float* ln_g, const float* ln_b, const float* b_s, const u32x2 (&uu)[8], const f32x4 (&wreg)[8], const u32x4 (&raw)[4], int cidx, int g, int tid) {
;     ...
;     {
;         const int i = wv * 16 + fr; const float bs = b_s[g * 128 + i];
;         bf16_t* up = Z + (size_t)(row0 + i) * INW + g * 128 + 4 * fq;
; #pragma unroll
;         for (int ct = 0; ct < 8; ++ct) {
;             u32x2 w; w.x = pk2(bf_lo(uu[ct].x) * (acc[ct][0] + bs), bf_hi(uu[ct].x) * (acc[ct][1] + bs)); w.y = pk2(bf_lo(uu[ct].y) * (acc[ct][2] + bs), bf_hi(uu[ct].y) * (acc[ct][3] + bs));
;             *(u32x2*)(up + 16 * ct) = w; }
;     }
	v_mfma_f32_16x16x32_bf16 v[168:171], v[208:211], v[92:95], v[168:171]
	s_waitcnt lgkmcnt(4)
	v_mfma_f32_16x16x32_bf16 v[172:175], v[212:215], v[92:95], v[172:175]
	s_waitcnt lgkmcnt(3)
	v_mfma_f32_16x16x32_bf16 v[176:179], v[224:227], v[92:95], v[176:179]
	s_waitcnt lgkmcnt(2)
	v_mfma_f32_16x16x32_bf16 v[180:183], v[228:231], v[92:95], v[180:183]
	s_waitcnt lgkmcnt(1)
	v_mfma_f32_16x16x32_bf16 v[184:187], v[232:235], v[92:95], v[184:187]
	s_waitcnt lgkmcnt(0)
	v_mfma_f32_16x16x32_bf16 v[188:191], v[236:239], v[92:95], v[188:191]
	s_waitcnt vmcnt(12)
	v_add_f32_e32 v160, v160, v7
	v_add_f32_e32 v161, v161, v7
	v_add_f32_e32 v162, v162, v7
	v_add_f32_e32 v163, v163, v7
	v_lshlrev_b32_e32 v8, 16, v112
	v_and_b32_e32 v9, 0xffff0000, v112
	v_lshlrev_b32_e32 v10, 16, v113
	v_and_b32_e32 v11, 0xffff0000, v113
	v_mul_f32_e32 v160, v8, v160
	v_mul_f32_e32 v161, v9, v161
	v_mul_f32_e32 v162, v10, v162
	v_mul_f32_e32 v163, v11, v163
	v_cvt_pk_bf16_f32 v12, v160, v161
	v_cvt_pk_bf16_f32 v13, v162, v163
	global_store_dwordx2 v2, v[12:13], s[20:21]
	s_nop 0
	v_add_f32_e32 v164, v164, v7
	v_add_f32_e32 v165, v165, v7
	v_add_f32_e32 v166, v166, v7
	v_add_f32_e32 v167, v167, v7
	v_lshlrev_b32_e32 v8, 16, v114
	v_and_b32_e32 v9, 0xffff0000, v114
	v_lshlrev_b32_e32 v10, 16, v115
	v_and_b32_e32 v11, 0xffff0000, v115
	v_mul_f32_e32 v164, v8, v164
	v_mul_f32_e32 v165, v9, v165
	v_mul_f32_e32 v166, v10, v166
	v_mul_f32_e32 v167, v11, v167
	v_cvt_pk_bf16_f32 v12, v164, v165
	v_cvt_pk_bf16_f32 v13, v166, v167
	global_store_dwordx2 v2, v[12:13], s[20:21] offset:32
	s_nop 0
	v_add_f32_e32 v168, v168, v7
	v_add_f32_e32 v169, v169, v7
	v_add_f32_e32 v170, v170, v7
	v_add_f32_e32 v171, v171, v7
	v_lshlrev_b32_e32 v8, 16, v116
	v_and_b32_e32 v9, 0xffff0000, v116
	v_lshlrev_b32_e32 v10, 16, v117
	v_and_b32_e32 v11, 0xffff0000, v117
	v_mul_f32_e32 v168, v8, v168
	v_mul_f32_e32 v169, v9, v169
	v_mul_f32_e32 v170, v10, v170
	v_mul_f32_e32 v171, v11, v171
	v_cvt_pk_bf16_f32 v12, v168, v169
	v_cvt_pk_bf16_f32 v13, v170, v171
	global_store_dwordx2 v2, v[12:13], s[20:21] offset:64
	s_nop 0
	v_add_f32_e32 v172, v172, v7
	v_add_f32_e32 v173, v173, v7
	v_add_f32_e32 v174, v174, v7
	v_add_f32_e32 v175, v175, v7
	v_lshlrev_b32_e32 v8, 16, v118
	v_and_b32_e32 v9, 0xffff0000, v118
	v_lshlrev_b32_e32 v10, 16, v119
	v_and_b32_e32 v11, 0xffff0000, v119
	v_mul_f32_e32 v172, v8, v172
	v_mul_f32_e32 v173, v9, v173
	v_mul_f32_e32 v174, v10, v174
	v_mul_f32_e32 v175, v11, v175
	v_cvt_pk_bf16_f32 v12, v172, v173
	v_cvt_pk_bf16_f32 v13, v174, v175
	global_store_dwordx2 v2, v[12:13], s[20:21] offset:96
	s_nop 0
	v_add_f32_e32 v176, v176, v7
	v_add_f32_e32 v177, v177, v7
	v_add_f32_e32 v178, v178, v7
	v_add_f32_e32 v179, v179, v7
	v_lshlrev_b32_e32 v8, 16, v120
	v_and_b32_e32 v9, 0xffff0000, v120
	v_lshlrev_b32_e32 v10, 16, v121
	v_and_b32_e32 v11, 0xffff0000, v121
	v_mul_f32_e32 v176, v8, v176
	v_mul_f32_e32 v177, v9, v177
	v_mul_f32_e32 v178, v10, v178
	v_mul_f32_e32 v179, v11, v179
	v_cvt_pk_bf16_f32 v12, v176, v177
	v_cvt_pk_bf16_f32 v13, v178, v179
	global_store_dwordx2 v2, v[12:13], s[20:21] offset:128
	s_nop 0
	v_add_f32_e32 v180, v180, v7
	v_add_f32_e32 v181, v181, v7
	v_add_f32_e32 v182, v182, v7
	v_add_f32_e32 v183, v183, v7
	v_lshlrev_b32_e32 v8, 16, v122
	v_and_b32_e32 v9, 0xffff0000, v122
	v_lshlrev_b32_e32 v10, 16, v123
	v_and_b32_e32 v11, 0xffff0000, v123
	v_mul_f32_e32 v180, v8, v180
	v_mul_f32_e32 v181, v9, v181
	v_mul_f32_e32 v182, v10, v182
	v_mul_f32_e32 v183, v11, v183
	v_cvt_pk_bf16_f32 v12, v180, v181
	v_cvt_pk_bf16_f32 v13, v182, v183
	global_store_dwordx2 v2, v[12:13], s[20:21] offset:160
	s_nop 0
	v_add_f32_e32 v184, v184, v7
	v_add_f32_e32 v185, v185, v7
	v_add_f32_e32 v186, v186, v7
	v_add_f32_e32 v187, v187, v7
	v_lshlrev_b32_e32 v8, 16, v124
	v_and_b32_e32 v9, 0xffff0000, v124
	v_lshlrev_b32_e32 v10, 16, v125
	v_and_b32_e32 v11, 0xffff0000, v125
	v_mul_f32_e32 v184, v8, v184
	v_mul_f32_e32 v185, v9, v185
	v_mul_f32_e32 v186, v10, v186
	v_mul_f32_e32 v187, v11, v187
	v_cvt_pk_bf16_f32 v12, v184, v185
	v_cvt_pk_bf16_f32 v13, v186, v187
	global_store_dwordx2 v2, v[12:13], s[20:21] offset:192
	s_nop 0
	v_add_f32_e32 v188, v188, v7
	v_add_f32_e32 v189, v189, v7
	v_add_f32_e32 v190, v190, v7
	v_add_f32_e32 v191, v191, v7
	v_lshlrev_b32_e32 v8, 16, v126
	v_and_b32_e32 v9, 0xffff0000, v126
	v_lshlrev_b32_e32 v10, 16, v127
	v_and_b32_e32 v11, 0xffff0000, v127
	v_mul_f32_e32 v188, v8, v188
	v_mul_f32_e32 v189, v9, v189
	v_mul_f32_e32 v190, v10, v190
	v_mul_f32_e32 v191, v11, v191
	v_cvt_pk_bf16_f32 v12, v188, v189
	v_cvt_pk_bf16_f32 v13, v190, v191
	global_store_dwordx2 v2, v[12:13], s[20:21] offset:224
	global_load_dwordx4 v[96:99], v1, s[26:27]
	global_load_dwordx4 v[100:103], v1, s[26:27] offset:16
	global_load_dwordx4 v[104:107], v1, s[26:27] offset:32
	global_load_dwordx4 v[108:111], v1, s[26:27] offset:48
	global_load_dwordx2 v[112:113], v2, s[26:27]
	global_load_dwordx2 v[114:115], v2, s[26:27] offset:32
	global_load_dwordx2 v[116:117], v2, s[26:27] offset:64
	global_load_dwordx2 v[118:119], v2, s[26:27] offset:96
	global_load_dwordx2 v[120:121], v2, s[26:27] offset:128
	global_load_dwordx2 v[122:123], v2, s[26:27] offset:160
	global_load_dwordx2 v[124:125], v2, s[26:27] offset:192
	global_load_dwordx2 v[126:127], v2, s[26:27] offset:224
	s_waitcnt vmcnt(28)
; #define LAS __attribute__((address_space(3)))
; __device__ __forceinline__ unsigned f2bf(float f) { unsigned u = __builtin_bit_cast(unsigned, f); return (u + 0x7fffu + ((u >> 16) & 1u)) >> 16; }
; __device__ __forceinline__ void gmlp_unit(LAS unsigned char* lds, bf16_t* Z, const float* ln_g, const float* ln_b, const float* b_s, const u32x2 (&uu)[8], const f32x4 (&wreg)[8], const u32x4 (&raw)[4], int cidx, int g, int tid) {
;     ...
;         const int j = tid >> 2, cq = (tid & 3) * 32;
;         float x[32];
; #pragma unroll
;         for (int q = 0; q < 4; ++q)
; #pragma unroll
;             for (int e = 0; e < 4; ++e) { x[8 * q + 2 * e] = bf_lo(raw[q][e]); x[8 * q + 2 * e + 1] = bf_hi(raw[q][e]); }
;         float s = 0.f;
; #pragma unroll
;         for (int c = 0; c < 32; ++c) s += x[c];
;         s += __shfl_xor(s, 1); s += __shfl_xor(s, 2);
;         const float mean = s * (1.f / 128.f); float q2 = 0.f;
; #pragma unroll
;         for (int c = 0; c < 32; ++c) { x[c] -= mean; q2 += x[c] * x[c]; }
;         q2 += __shfl_xor(q2, 1); q2 += __shfl_xor(q2, 2);
;         const float rstd = __builtin_amdgcn_rsqf(q2 * (1.f / 128.f) + EPS);
;         const float* gp = ln_g + g * 128 + cq; const float* bp = ln_b + g * 128 + cq;
; #pragma unroll
;         for (int c4 = 0; c4 < 8; ++c4) { const f32x4 gg = *(const f32x4*)(gp + 4 * c4), bb = *(const f32x4*)(bp + 4 * c4);
; #pragma unroll
;             for (int e = 0; e < 4; ++e) { const int c = 4 * c4 + e; const float y = x[c] * rstd * gg[e] + bb[e];
;                 *(LAS unsigned short*)(VT + (cq + c) * LSTR + j * 2) = (unsigned short)f2bf(y); } }
	v_lshlrev_b32_e32 v160, 16, v128
	v_and_b32_e32 v161, 0xffff0000, v128
	v_lshlrev_b32_e32 v162, 16, v129
	v_and_b32_e32 v163, 0xffff0000, v129
	v_lshlrev_b32_e32 v164, 16, v130
	v_and_b32_e32 v165, 0xffff0000, v130
	v_lshlrev_b32_e32 v166, 16, v131
	v_and_b32_e32 v167, 0xffff0000, v131
	v_lshlrev_b32_e32 v168, 16, v132
	v_and_b32_e32 v169, 0xffff0000, v132
	v_lshlrev_b32_e32 v170, 16, v133
	v_and_b32_e32 v171, 0xffff0000, v133
	v_lshlrev_b32_e32 v172, 16, v134
	v_and_b32_e32 v173, 0xffff0000, v134
	v_lshlrev_b32_e32 v174, 16, v135
	v_and_b32_e32 v175, 0xffff0000, v135
	v_lshlrev_b32_e32 v176, 16, v136
	v_and_b32_e32 v177, 0xffff0000, v136
	v_lshlrev_b32_e32 v178, 16, v137
	v_and_b32_e32 v179, 0xffff0000, v137
	v_lshlrev_b32_e32 v180, 16, v138
	v_and_b32_e32 v181, 0xffff0000, v138
	v_lshlrev_b32_e32 v182, 16, v139
	v_and_b32_e32 v183, 0xffff0000, v139
	v_lshlrev_b32_e32 v184, 16, v140
	v_and_b32_e32 v185, 0xffff0000, v140
	v_lshlrev_b32_e32 v186, 16, v141
	v_and_b32_e32 v187, 0xffff0000, v141
	v_lshlrev_b32_e32 v188, 16, v142
	v_and_b32_e32 v189, 0xffff0000, v142
	v_lshlrev_b32_e32 v190, 16, v143
	v_and_b32_e32 v191, 0xffff0000, v143
	v_add_f32_e32 v8, v160, v164
	v_add_f32_e32 v9, v161, v165
	v_add_f32_e32 v10, v162, v166
	v_add_f32_e32 v11, v163, v167
	v_add_f32_e32 v8, v8, v168
	v_add_f32_e32 v9, v9, v169
	v_add_f32_e32 v10, v10, v170
	v_add_f32_e32 v11, v11, v171
	v_add_f32_e32 v8, v8, v172
	v_add_f32_e32 v9, v9, v173
	v_add_f32_e32 v10, v10, v174
	v_add_f32_e32 v11, v11, v175
	v_add_f32_e32 v8, v8, v176
	v_add_f32_e32 v9, v9, v177
	v_add_f32_e32 v10, v10, v178
	v_add_f32_e32 v11, v11, v179
	v_add_f32_e32 v8, v8, v180
	v_add_f32_e32 v9, v9, v181
	v_add_f32_e32 v10, v10, v182
	v_add_f32_e32 v11, v11, v183
	v_add_f32_e32 v8, v8, v184
	v_add_f32_e32 v9, v9, v185
	v_add_f32_e32 v10, v10, v186
	v_add_f32_e32 v11, v11, v187
	v_add_f32_e32 v8, v8, v188
	v_add_f32_e32 v9, v9, v189
	v_add_f32_e32 v10, v10, v190
	v_add_f32_e32 v11, v11, v191
	v_add_f32_e32 v8, v8, v9
	v_add_f32_e32 v10, v10, v11
	v_add_f32_e32 v8, v8, v10
	s_nop 1
	v_add_f32_dpp v8, v8, v8 quad_perm:[1,0,3,2] row_mask:0xf bank_mask:0xf
	s_nop 1
	v_add_f32_dpp v8, v8, v8 quad_perm:[2,3,0,1] row_mask:0xf bank_mask:0xf
	v_mul_f32_e32 v8, 0xbc000000, v8
	v_add_f32_e32 v160, v160, v8
	v_add_f32_e32 v161, v161, v8
	v_add_f32_e32 v162, v162, v8
	v_add_f32_e32 v163, v163, v8
	v_add_f32_e32 v164, v164, v8
	v_add_f32_e32 v165, v165, v8
	v_add_f32_e32 v166, v166, v8
	v_add_f32_e32 v167, v167, v8
	v_add_f32_e32 v168, v168, v8
	v_add_f32_e32 v169, v169, v8
	v_add_f32_e32 v170, v170, v8
	v_add_f32_e32 v171, v171, v8
	v_add_f32_e32 v172, v172, v8
	v_add_f32_e32 v173, v173, v8
	v_add_f32_e32 v174, v174, v8
	v_add_f32_e32 v175, v175, v8
	v_add_f32_e32 v176, v176, v8
	v_add_f32_e32 v177, v177, v8
	v_add_f32_e32 v178, v178, v8
	v_add_f32_e32 v179, v179, v8
	v_add_f32_e32 v180, v180, v8
	v_add_f32_e32 v181, v181, v8
	v_add_f32_e32 v182, v182, v8
	v_add_f32_e32 v183, v183, v8
	v_add_f32_e32 v184, v184, v8
	v_add_f32_e32 v185, v185, v8
	v_add_f32_e32 v186, v186, v8
	v_add_f32_e32 v187, v187, v8
	v_add_f32_e32 v188, v188, v8
	v_add_f32_e32 v189, v189, v8
	v_add_f32_e32 v190, v190, v8
	v_add_f32_e32 v191, v191, v8
	v_mul_f32_e32 v8, v160, v160
	v_mul_f32_e32 v9, v161, v161
	v_mul_f32_e32 v10, v162, v162
	v_mul_f32_e32 v11, v163, v163
	v_fmac_f32_e32 v8, v164, v164
	v_fmac_f32_e32 v9, v165, v165
	v_fmac_f32_e32 v10, v166, v166
	v_fmac_f32_e32 v11, v167, v167
	v_fmac_f32_e32 v8, v168, v168
	v_fmac_f32_e32 v9, v169, v169
	v_fmac_f32_e32 v10, v170, v170
	v_fmac_f32_e32 v11, v171, v171
	v_fmac_f32_e32 v8, v172, v172
	v_fmac_f32_e32 v9, v173, v173
	v_fmac_f32_e32 v10, v174, v174
	v_fmac_f32_e32 v11, v175, v175
	v_fmac_f32_e32 v8, v176, v176
	v_fmac_f32_e32 v9, v177, v177
	v_fmac_f32_e32 v10, v178, v178
	v_fmac_f32_e32 v11, v179, v179
	v_fmac_f32_e32 v8, v180, v180
	v_fmac_f32_e32 v9, v181, v181
	v_fmac_f32_e32 v10, v182, v182
	v_fmac_f32_e32 v11, v183, v183
	v_fmac_f32_e32 v8, v184, v184
	v_fmac_f32_e32 v9, v185, v185
	v_fmac_f32_e32 v10, v186, v186
	v_fmac_f32_e32 v11, v187, v187
	v_fmac_f32_e32 v8, v188, v188
	v_fmac_f32_e32 v9, v189, v189
	v_fmac_f32_e32 v10, v190, v190
	v_fmac_f32_e32 v11, v191, v191
	v_add_f32_e32 v8, v8, v9
	v_add_f32_e32 v10, v10, v11
	v_add_f32_e32 v8, v8, v10
	s_nop 1
	v_add_f32_dpp v8, v8, v8 quad_perm:[1,0,3,2] row_mask:0xf bank_mask:0xf
	s_nop 1
	v_add_f32_dpp v8, v8, v8 quad_perm:[2,3,0,1] row_mask:0xf bank_mask:0xf
	v_fmamk_f32 v8, v8, 0x3c000000, v219
	v_rsq_f32_e32 v8, v8
	s_nop 0
	v_mul_f32_e32 v160, v160, v8
	v_fma_f32 v160, v16, v160, v48
	v_bfe_u32 v9, v160, 16, 1
	v_add3_u32 v160, v160, v9, s81
	ds_write_b16_d16_hi v3, v160 offset:34816
	v_mul_f32_e32 v161, v161, v8
	v_fma_f32 v161, v17, v161, v49
	v_bfe_u32 v10, v161, 16, 1
	v_add3_u32 v161, v161, v10, s81
	ds_write_b16_d16_hi v3, v161 offset:35088
	v_mul_f32_e32 v162, v162, v8
	v_fma_f32 v162, v18, v162, v50
	v_bfe_u32 v9, v162, 16, 1
	v_add3_u32 v162, v162, v9, s81
	ds_write_b16_d16_hi v3, v162 offset:35360
	v_mul_f32_e32 v163, v163, v8
	v_fma_f32 v163, v19, v163, v51
	v_bfe_u32 v10, v163, 16, 1
	v_add3_u32 v163, v163, v10, s81
	ds_write_b16_d16_hi v3, v163 offset:35632
	v_mul_f32_e32 v164, v164, v8
	v_fma_f32 v164, v20, v164, v52
	v_bfe_u32 v9, v164, 16, 1
	v_add3_u32 v164, v164, v9, s81
	ds_write_b16_d16_hi v3, v164 offset:35904
	v_mul_f32_e32 v165, v165, v8
	v_fma_f32 v165, v21, v165, v53
	v_bfe_u32 v10, v165, 16, 1
	v_add3_u32 v165, v165, v10, s81
	ds_write_b16_d16_hi v3, v165 offset:36176
	v_mul_f32_e32 v166, v166, v8
	v_fma_f32 v166, v22, v166, v54
	v_bfe_u32 v9, v166, 16, 1
	v_add3_u32 v166, v166, v9, s81
; #define LAS __attribute__((address_space(3)))
; __device__ __forceinline__ unsigned f2bf(float f) { unsigned u = __builtin_bit_cast(unsigned, f); return (u + 0x7fffu + ((u >> 16) & 1u)) >> 16; }
; __device__ __forceinline__ unsigned pk2(float lo, float hi) { return pg8::cvt_pk_bf16(lo, hi); }
; __device__ __forceinline__ void gmlp_unit(LAS unsigned char* lds, bf16_t* Z, const float* ln_g, const float* ln_b, const float* b_s, const u32x2 (&uu)[8], const f32x4 (&wreg)[8], const u32x4 (&raw)[4], int cidx, int g, int tid) {
;     ...
;             for (int e = 0; e < 4; ++e) { const int c = 4 * c4 + e; const float y = x[c] * rstd * gg[e] + bb[e];
;                 *(LAS unsigned short*)(VT + (cq + c) * LSTR + j * 2) = (unsigned short)f2bf(y); } }
;     }
;     {
;         const int i = tid >> 2, jq = (tid & 3) * 32;
; #pragma unroll
;         for (int q = 0; q < 4; ++q) { f32x4 a = wreg[2 * q], b = wreg[2 * q + 1];
;             const int j0 = jq + 8 * q;
; #pragma unroll
;             for (int e = 0; e < 4; ++e) { if (j0 + e > i) a[e] = 0.f; if (j0 + 4 + e > i) b[e] = 0.f; }
;             u32x4 w; w.x = pk2(a[0], a[1]); w.y = pk2(a[2], a[3]); w.z = pk2(b[0], b[1]); w.w = pk2(b[2], b[3]);
;             *(LAS u32x4*)(WS + i * LSTR + j0 * 2) = w; }
;     }
;     __syncthreads();
;     const int wv = tid >> 6, lane = tid & 63, fr = lane & 15, fq = lane >> 4;
;     f32x4 acc[8];
; #pragma unroll
;     for (int ct = 0; ct < 8; ++ct) acc[ct] = (f32x4){0.f, 0.f, 0.f, 0.f};
; #pragma unroll
;     for (int ks = 0; ks < 4; ++ks) {
;         const bf16x8 bw = *(const LAS bf16x8*)(WS + (wv * 16 + fr) * LSTR + (ks * 32 + fq * 8) * 2);
; #pragma unroll
;         for (int ct = 0; ct < 8; ++ct) { const bf16x8 av = *(const LAS bf16x8*)(VT + (ct * 16 + fr) * LSTR + (ks * 32 + fq * 8) * 2);
;             acc[ct] = __builtin_amdgcn_mfma_f32_16x16x32_bf16(av, bw, acc[ct], 0, 0, 0); }
	ds_write_b16_d16_hi v3, v166 offset:36448
	v_mul_f32_e32 v167, v167, v8
	v_fma_f32 v167, v23, v167, v55
	v_bfe_u32 v10, v167, 16, 1
	v_add3_u32 v167, v167, v10, s81
	ds_write_b16_d16_hi v3, v167 offset:36720
	v_mul_f32_e32 v168, v168, v8
	v_fma_f32 v168, v24, v168, v56
	v_bfe_u32 v9, v168, 16, 1
	v_add3_u32 v168, v168, v9, s81
	ds_write_b16_d16_hi v3, v168 offset:36992
	v_mul_f32_e32 v169, v169, v8
	v_fma_f32 v169, v25, v169, v57
	v_bfe_u32 v10, v169, 16, 1
	v_add3_u32 v169, v169, v10, s81
	ds_write_b16_d16_hi v3, v169 offset:37264
	v_mul_f32_e32 v170, v170, v8
	v_fma_f32 v170, v26, v170, v58
	v_bfe_u32 v9, v170, 16, 1
	v_add3_u32 v170, v170, v9, s81
	ds_write_b16_d16_hi v3, v170 offset:37536
	v_mul_f32_e32 v171, v171, v8
	v_fma_f32 v171, v27, v171, v59
	v_bfe_u32 v10, v171, 16, 1
	v_add3_u32 v171, v171, v10, s81
	ds_write_b16_d16_hi v3, v171 offset:37808
	v_mul_f32_e32 v172, v172, v8
	v_fma_f32 v172, v28, v172, v60
	v_bfe_u32 v9, v172, 16, 1
	v_add3_u32 v172, v172, v9, s81
	ds_write_b16_d16_hi v3, v172 offset:38080
	v_mul_f32_e32 v173, v173, v8
	v_fma_f32 v173, v29, v173, v61
	v_bfe_u32 v10, v173, 16, 1
	v_add3_u32 v173, v173, v10, s81
	ds_write_b16_d16_hi v3, v173 offset:38352
	v_mul_f32_e32 v174, v174, v8
	v_fma_f32 v174, v30, v174, v62
	v_bfe_u32 v9, v174, 16, 1
	v_add3_u32 v174, v174, v9, s81
	ds_write_b16_d16_hi v3, v174 offset:38624
	v_mul_f32_e32 v175, v175, v8
	v_fma_f32 v175, v31, v175, v63
	v_bfe_u32 v10, v175, 16, 1
	v_add3_u32 v175, v175, v10, s81
	ds_write_b16_d16_hi v3, v175 offset:38896
	v_mul_f32_e32 v176, v176, v8
	v_fma_f32 v176, v32, v176, v64
	v_bfe_u32 v9, v176, 16, 1
	v_add3_u32 v176, v176, v9, s81
	ds_write_b16_d16_hi v3, v176 offset:39168
	v_mul_f32_e32 v177, v177, v8
	v_fma_f32 v177, v33, v177, v65
	v_bfe_u32 v10, v177, 16, 1
	v_add3_u32 v177, v177, v10, s81
	ds_write_b16_d16_hi v3, v177 offset:39440
	v_mul_f32_e32 v178, v178, v8
	v_fma_f32 v178, v34, v178, v66
	v_bfe_u32 v9, v178, 16, 1
	v_add3_u32 v178, v178, v9, s81
	ds_write_b16_d16_hi v3, v178 offset:39712
	v_mul_f32_e32 v179, v179, v8
	v_fma_f32 v179, v35, v179, v67
	v_bfe_u32 v10, v179, 16, 1
	v_add3_u32 v179, v179, v10, s81
	ds_write_b16_d16_hi v3, v179 offset:39984
	v_mul_f32_e32 v180, v180, v8
	v_fma_f32 v180, v36, v180, v68
	v_bfe_u32 v9, v180, 16, 1
	v_add3_u32 v180, v180, v9, s81
	ds_write_b16_d16_hi v3, v180 offset:40256
	v_mul_f32_e32 v181, v181, v8
	v_fma_f32 v181, v37, v181, v69
	v_bfe_u32 v10, v181, 16, 1
	v_add3_u32 v181, v181, v10, s81
	ds_write_b16_d16_hi v3, v181 offset:40528
	v_mul_f32_e32 v182, v182, v8
	v_fma_f32 v182, v38, v182, v70
	v_bfe_u32 v9, v182, 16, 1
	v_add3_u32 v182, v182, v9, s81
	ds_write_b16_d16_hi v3, v182 offset:40800
	v_mul_f32_e32 v183, v183, v8
	v_fma_f32 v183, v39, v183, v71
	v_bfe_u32 v10, v183, 16, 1
	v_add3_u32 v183, v183, v10, s81
	ds_write_b16_d16_hi v3, v183 offset:41072
	v_mul_f32_e32 v184, v184, v8
	v_fma_f32 v184, v40, v184, v72
	v_bfe_u32 v9, v184, 16, 1
	v_add3_u32 v184, v184, v9, s81
	ds_write_b16_d16_hi v3, v184 offset:41344
	v_mul_f32_e32 v185, v185, v8
	v_fma_f32 v185, v41, v185, v73
	v_bfe_u32 v10, v185, 16, 1
	v_add3_u32 v185, v185, v10, s81
	ds_write_b16_d16_hi v3, v185 offset:41616
	v_mul_f32_e32 v186, v186, v8
	v_fma_f32 v186, v42, v186, v74
	v_bfe_u32 v9, v186, 16, 1
	v_add3_u32 v186, v186, v9, s81
	ds_write_b16_d16_hi v3, v186 offset:41888
	v_mul_f32_e32 v187, v187, v8
	v_fma_f32 v187, v43, v187, v75
	v_bfe_u32 v10, v187, 16, 1
	v_add3_u32 v187, v187, v10, s81
	ds_write_b16_d16_hi v3, v187 offset:42160
	v_mul_f32_e32 v188, v188, v8
	v_fma_f32 v188, v44, v188, v76
	v_bfe_u32 v9, v188, 16, 1
	v_add3_u32 v188, v188, v9, s81
	ds_write_b16_d16_hi v3, v188 offset:42432
	v_mul_f32_e32 v189, v189, v8
	v_fma_f32 v189, v45, v189, v77
	v_bfe_u32 v10, v189, 16, 1
	v_add3_u32 v189, v189, v10, s81
	ds_write_b16_d16_hi v3, v189 offset:42704
	v_mul_f32_e32 v190, v190, v8
	v_fma_f32 v190, v46, v190, v78
	v_bfe_u32 v9, v190, 16, 1
	v_add3_u32 v190, v190, v9, s81
	ds_write_b16_d16_hi v3, v190 offset:42976
	v_mul_f32_e32 v191, v191, v8
	v_fma_f32 v191, v47, v191, v79
	v_bfe_u32 v10, v191, 16, 1
	v_add3_u32 v191, v191, v10, s81
	ds_write_b16_d16_hi v3, v191 offset:43248
	s_waitcnt lgkmcnt(0)
	s_barrier
	ds_read_b128 v[200:203], v4 offset:34816
	ds_read_b128 v[204:207], v4 offset:39168
	ds_read_b128 v[208:211], v4 offset:43584
	ds_read_b128 v[212:215], v4 offset:47936
	ds_read_b128 v[224:227], v4 offset:52352
	ds_read_b128 v[228:231], v4 offset:56704
	ds_read_b128 v[232:235], v4 offset:61120
	ds_read_b128 v[236:239], v4 offset:65472
	s_waitcnt lgkmcnt(7)
	v_mfma_f32_16x16x32_bf16 v[160:163], v[200:203], v[80:83], 0
	ds_read_b128 v[200:203], v4 offset:34880
	s_waitcnt lgkmcnt(7)
	v_mfma_f32_16x16x32_bf16 v[164:167], v[204:207], v[80:83], 0
	ds_read_b128 v[204:207], v4 offset:39232
	s_waitcnt lgkmcnt(7)
	v_mfma_f32_16x16x32_bf16 v[168:171], v[208:211], v[80:83], 0
	ds_read_b128 v[208:211], v4 offset:43520
	s_waitcnt lgkmcnt(7)
	v_mfma_f32_16x16x32_bf16 v[172:175], v[212:215], v[80:83], 0
	ds_read_b128 v[212:215], v4 offset:47872
	s_waitcnt lgkmcnt(7)
	v_mfma_f32_16x16x32_bf16 v[176:179], v[224:227], v[80:83], 0
	ds_read_b128 v[224:227], v4 offset:52416
	s_waitcnt lgkmcnt(7)
	v_mfma_f32_16x16x32_bf16 v[180:183], v[228:231], v[80:83], 0
	ds_read_b128 v[228:231], v4 offset:56768
	s_waitcnt lgkmcnt(7)
	v_mfma_f32_16x16x32_bf16 v[184:187], v[232:235], v[80:83], 0
	ds_read_b128 v[232:235], v4 offset:61056
	s_waitcnt lgkmcnt(7)
	v_mfma_f32_16x16x32_bf16 v[188:191], v[236:239], v[80:83], 0
	ds_read_b128 v[236:239], v4 offset:65408
	s_waitcnt lgkmcnt(7)
	v_mfma_f32_16x16x32_bf16 v[160:163], v[200:203], v[84:87], v[160:163]
	ds_read_b128 v[200:203], v4 offset:34944
	s_waitcnt lgkmcnt(7)
; #define LAS __attribute__((address_space(3)))
; __device__ __forceinline__ unsigned pk2(float lo, float hi) { return pg8::cvt_pk_bf16(lo, hi); }
; __device__ __forceinline__ void gmlp_unit(LAS unsigned char* lds, bf16_t* Z, const float* ln_g, const float* ln_b, const float* b_s, const u32x2 (&uu)[8], const f32x4 (&wreg)[8], const u32x4 (&raw)[4], int cidx, int g, int tid) {
;     ...
;     for (int ks = 0; ks < 4; ++ks) {
;         const bf16x8 bw = *(const LAS bf16x8*)(WS + (wv * 16 + fr) * LSTR + (ks * 32 + fq * 8) * 2);
; #pragma unroll
;         for (int ct = 0; ct < 8; ++ct) { const bf16x8 av = *(const LAS bf16x8*)(VT + (ct * 16 + fr) * LSTR + (ks * 32 + fq * 8) * 2);
;             acc[ct] = __builtin_amdgcn_mfma_f32_16x16x32_bf16(av, bw, acc[ct], 0, 0, 0); }
;     }
;     {
;         const int i = wv * 16 + fr; const float bs = b_s[g * 128 + i];
;         bf16_t* up = Z + (size_t)(row0 + i) * INW + g * 128 + 4 * fq;
; #pragma unroll
;         for (int ct = 0; ct < 8; ++ct) {
;             u32x2 w; w.x = pk2(bf_lo(uu[ct].x) * (acc[ct][0] + bs), bf_hi(uu[ct].x) * (acc[ct][1] + bs)); w.y = pk2(bf_lo(uu[ct].y) * (acc[ct][2] + bs), bf_hi(uu[ct].y) * (acc[ct][3] + bs));
;             *(u32x2*)(up + 16 * ct) = w; }
;     }
	v_mfma_f32_16x16x32_bf16 v[164:167], v[204:207], v[84:87], v[164:167]
	ds_read_b128 v[204:207], v4 offset:39296
	s_waitcnt lgkmcnt(7)
	v_mfma_f32_16x16x32_bf16 v[168:171], v[208:211], v[84:87], v[168:171]
	ds_read_b128 v[208:211], v4 offset:43712
	s_waitcnt lgkmcnt(7)
	v_mfma_f32_16x16x32_bf16 v[172:175], v[212:215], v[84:87], v[172:175]
	ds_read_b128 v[212:215], v4 offset:48064
	s_waitcnt lgkmcnt(7)
	v_mfma_f32_16x16x32_bf16 v[176:179], v[224:227], v[84:87], v[176:179]
	ds_read_b128 v[224:227], v4 offset:52224
	s_waitcnt lgkmcnt(7)
	v_mfma_f32_16x16x32_bf16 v[180:183], v[228:231], v[84:87], v[180:183]
	ds_read_b128 v[228:231], v4 offset:56576
	s_waitcnt lgkmcnt(7)
	v_mfma_f32_16x16x32_bf16 v[184:187], v[232:235], v[84:87], v[184:187]
	ds_read_b128 v[232:235], v4 offset:60992
	s_waitcnt lgkmcnt(7)
	v_mfma_f32_16x16x32_bf16 v[188:191], v[236:239], v[84:87], v[188:191]
	ds_read_b128 v[236:239], v4 offset:65344
	s_waitcnt lgkmcnt(7)
	v_mfma_f32_16x16x32_bf16 v[160:163], v[200:203], v[88:91], v[160:163]
	ds_read_b128 v[200:203], v4 offset:35008
	s_waitcnt lgkmcnt(7)
	v_mfma_f32_16x16x32_bf16 v[164:167], v[204:207], v[88:91], v[164:167]
	ds_read_b128 v[204:207], v4 offset:39360
	s_waitcnt lgkmcnt(7)
	v_mfma_f32_16x16x32_bf16 v[168:171], v[208:211], v[88:91], v[168:171]
	ds_read_b128 v[208:211], v4 offset:43648
	s_waitcnt lgkmcnt(7)
	v_mfma_f32_16x16x32_bf16 v[172:175], v[212:215], v[88:91], v[172:175]
	ds_read_b128 v[212:215], v4 offset:48000
	s_waitcnt lgkmcnt(7)
	v_mfma_f32_16x16x32_bf16 v[176:179], v[224:227], v[88:91], v[176:179]
	ds_read_b128 v[224:227], v4 offset:52288
	s_waitcnt lgkmcnt(7)
	v_mfma_f32_16x16x32_bf16 v[180:183], v[228:231], v[88:91], v[180:183]
	ds_read_b128 v[228:231], v4 offset:56640
	s_waitcnt lgkmcnt(7)
	v_mfma_f32_16x16x32_bf16 v[184:187], v[232:235], v[88:91], v[184:187]
	ds_read_b128 v[232:235], v4 offset:60928
	s_waitcnt lgkmcnt(7)
	v_mfma_f32_16x16x32_bf16 v[188:191], v[236:239], v[88:91], v[188:191]
	ds_read_b128 v[236:239], v4 offset:65280
	s_waitcnt lgkmcnt(7)
	v_mfma_f32_16x16x32_bf16 v[160:163], v[200:203], v[92:95], v[160:163]
	s_waitcnt lgkmcnt(6)
	v_mfma_f32_16x16x32_bf16 v[164:167], v[204:207], v[92:95], v[164:167]
	s_waitcnt lgkmcnt(5)
	v_mfma_f32_16x16x32_bf16 v[168:171], v[208:211], v[92:95], v[168:171]
	s_waitcnt lgkmcnt(4)
	v_mfma_f32_16x16x32_bf16 v[172:175], v[212:215], v[92:95], v[172:175]
	s_waitcnt lgkmcnt(3)
	v_mfma_f32_16x16x32_bf16 v[176:179], v[224:227], v[92:95], v[176:179]
	s_waitcnt lgkmcnt(2)
	v_mfma_f32_16x16x32_bf16 v[180:183], v[228:231], v[92:95], v[180:183]
	s_waitcnt lgkmcnt(1)
	v_mfma_f32_16x16x32_bf16 v[184:187], v[232:235], v[92:95], v[184:187]
	s_waitcnt lgkmcnt(0)
	v_mfma_f32_16x16x32_bf16 v[188:191], v[236:239], v[92:95], v[188:191]
	s_waitcnt vmcnt(20)
	v_add_f32_e32 v160, v160, v7
	v_add_f32_e32 v161, v161, v7
	v_add_f32_e32 v162, v162, v7
	v_add_f32_e32 v163, v163, v7
	v_lshlrev_b32_e32 v8, 16, v144
	v_and_b32_e32 v9, 0xffff0000, v144
	v_lshlrev_b32_e32 v10, 16, v145
	v_and_b32_e32 v11, 0xffff0000, v145
	v_mul_f32_e32 v160, v8, v160
	v_mul_f32_e32 v161, v9, v161
	v_mul_f32_e32 v162, v10, v162
	v_mul_f32_e32 v163, v11, v163
	v_cvt_pk_bf16_f32 v12, v160, v161
	v_cvt_pk_bf16_f32 v13, v162, v163
	global_store_dwordx2 v2, v[12:13], s[24:25]
	s_nop 0
	v_add_f32_e32 v164, v164, v7
	v_add_f32_e32 v165, v165, v7
	v_add_f32_e32 v166, v166, v7
	v_add_f32_e32 v167, v167, v7
	v_lshlrev_b32_e32 v8, 16, v146
	v_and_b32_e32 v9, 0xffff0000, v146
	v_lshlrev_b32_e32 v10, 16, v147
	v_and_b32_e32 v11, 0xffff0000, v147
	v_mul_f32_e32 v164, v8, v164
	v_mul_f32_e32 v165, v9, v165
	v_mul_f32_e32 v166, v10, v166
	v_mul_f32_e32 v167, v11, v167
	v_cvt_pk_bf16_f32 v12, v164, v165
	v_cvt_pk_bf16_f32 v13, v166, v167
	global_store_dwordx2 v2, v[12:13], s[24:25] offset:32
	s_nop 0
	v_add_f32_e32 v168, v168, v7
	v_add_f32_e32 v169, v169, v7
	v_add_f32_e32 v170, v170, v7
	v_add_f32_e32 v171, v171, v7
	v_lshlrev_b32_e32 v8, 16, v148
	v_and_b32_e32 v9, 0xffff0000, v148
	v_lshlrev_b32_e32 v10, 16, v149
	v_and_b32_e32 v11, 0xffff0000, v149
	v_mul_f32_e32 v168, v8, v168
	v_mul_f32_e32 v169, v9, v169
	v_mul_f32_e32 v170, v10, v170
	v_mul_f32_e32 v171, v11, v171
	v_cvt_pk_bf16_f32 v12, v168, v169
	v_cvt_pk_bf16_f32 v13, v170, v171
	global_store_dwordx2 v2, v[12:13], s[24:25] offset:64
	s_nop 0
	v_add_f32_e32 v172, v172, v7
	v_add_f32_e32 v173, v173, v7
	v_add_f32_e32 v174, v174, v7
	v_add_f32_e32 v175, v175, v7
	v_lshlrev_b32_e32 v8, 16, v150
	v_and_b32_e32 v9, 0xffff0000, v150
	v_lshlrev_b32_e32 v10, 16, v151
	v_and_b32_e32 v11, 0xffff0000, v151
	v_mul_f32_e32 v172, v8, v172
	v_mul_f32_e32 v173, v9, v173
	v_mul_f32_e32 v174, v10, v174
	v_mul_f32_e32 v175, v11, v175
	v_cvt_pk_bf16_f32 v12, v172, v173
	v_cvt_pk_bf16_f32 v13, v174, v175
	global_store_dwordx2 v2, v[12:13], s[24:25] offset:96
	s_nop 0
	v_add_f32_e32 v176, v176, v7
	v_add_f32_e32 v177, v177, v7
	v_add_f32_e32 v178, v178, v7
	v_add_f32_e32 v179, v179, v7
	v_lshlrev_b32_e32 v8, 16, v152
	v_and_b32_e32 v9, 0xffff0000, v152
	v_lshlrev_b32_e32 v10, 16, v153
	v_and_b32_e32 v11, 0xffff0000, v153
	v_mul_f32_e32 v176, v8, v176
	v_mul_f32_e32 v177, v9, v177
	v_mul_f32_e32 v178, v10, v178
	v_mul_f32_e32 v179, v11, v179
	v_cvt_pk_bf16_f32 v12, v176, v177
	v_cvt_pk_bf16_f32 v13, v178, v179
	global_store_dwordx2 v2, v[12:13], s[24:25] offset:128
	s_nop 0
	v_add_f32_e32 v180, v180, v7
	v_add_f32_e32 v181, v181, v7
	v_add_f32_e32 v182, v182, v7
	v_add_f32_e32 v183, v183, v7
	v_lshlrev_b32_e32 v8, 16, v154
	v_and_b32_e32 v9, 0xffff0000, v154
	v_lshlrev_b32_e32 v10, 16, v155
	v_and_b32_e32 v11, 0xffff0000, v155
	v_mul_f32_e32 v180, v8, v180
	v_mul_f32_e32 v181, v9, v181
; __device__ __forceinline__ unsigned pk2(float lo, float hi) { return pg8::cvt_pk_bf16(lo, hi); }
; __device__ __forceinline__ void gmlp_unit(LAS unsigned char* lds, bf16_t* Z, const float* ln_g, const float* ln_b, const float* b_s, const u32x2 (&uu)[8], const f32x4 (&wreg)[8], const u32x4 (&raw)[4], int cidx, int g, int tid) {
;     ...
;         const int j = tid >> 2, cq = (tid & 3) * 32;
;         float x[32];
; #pragma unroll
;         for (int q = 0; q < 4; ++q)
; #pragma unroll
;             for (int e = 0; e < 4; ++e) { x[8 * q + 2 * e] = bf_lo(raw[q][e]); x[8 * q + 2 * e + 1] = bf_hi(raw[q][e]); }
;         float s = 0.f;
; #pragma unroll
;         for (int c = 0; c < 32; ++c) s += x[c];
;         s += __shfl_xor(s, 1); s += __shfl_xor(s, 2);
;         const float mean = s * (1.f / 128.f); float q2 = 0.f;
; #pragma unroll
;         for (int c = 0; c < 32; ++c) { x[c] -= mean; q2 += x[c] * x[c]; }
;         q2 += __shfl_xor(q2, 1); q2 += __shfl_xor(q2, 2);
;         const float rstd = __builtin_amdgcn_rsqf(q2 * (1.f / 128.f) + EPS);
;     ...
;     {
;         const int i = wv * 16 + fr; const float bs = b_s[g * 128 + i];
;         bf16_t* up = Z + (size_t)(row0 + i) * INW + g * 128 + 4 * fq;
; #pragma unroll
;         for (int ct = 0; ct < 8; ++ct) {
;             u32x2 w; w.x = pk2(bf_lo(uu[ct].x) * (acc[ct][0] + bs), bf_hi(uu[ct].x) * (acc[ct][1] + bs)); w.y = pk2(bf_lo(uu[ct].y) * (acc[ct][2] + bs), bf_hi(uu[ct].y) * (acc[ct][3] + bs));
;             *(u32x2*)(up + 16 * ct) = w; }
;     }
	v_mul_f32_e32 v182, v10, v182
	v_mul_f32_e32 v183, v11, v183
	v_cvt_pk_bf16_f32 v12, v180, v181
	v_cvt_pk_bf16_f32 v13, v182, v183
	global_store_dwordx2 v2, v[12:13], s[24:25] offset:160
	s_nop 0
	v_add_f32_e32 v184, v184, v7
	v_add_f32_e32 v185, v185, v7
	v_add_f32_e32 v186, v186, v7
	v_add_f32_e32 v187, v187, v7
	v_lshlrev_b32_e32 v8, 16, v156
	v_and_b32_e32 v9, 0xffff0000, v156
	v_lshlrev_b32_e32 v10, 16, v157
	v_and_b32_e32 v11, 0xffff0000, v157
	v_mul_f32_e32 v184, v8, v184
	v_mul_f32_e32 v185, v9, v185
	v_mul_f32_e32 v186, v10, v186
	v_mul_f32_e32 v187, v11, v187
	v_cvt_pk_bf16_f32 v12, v184, v185
	v_cvt_pk_bf16_f32 v13, v186, v187
	global_store_dwordx2 v2, v[12:13], s[24:25] offset:192
	s_nop 0
	v_add_f32_e32 v188, v188, v7
	v_add_f32_e32 v189, v189, v7
	v_add_f32_e32 v190, v190, v7
	v_add_f32_e32 v191, v191, v7
	v_lshlrev_b32_e32 v8, 16, v158
	v_and_b32_e32 v9, 0xffff0000, v158
	v_lshlrev_b32_e32 v10, 16, v159
	v_and_b32_e32 v11, 0xffff0000, v159
	v_mul_f32_e32 v188, v8, v188
	v_mul_f32_e32 v189, v9, v189
	v_mul_f32_e32 v190, v10, v190
	v_mul_f32_e32 v191, v11, v191
	v_cvt_pk_bf16_f32 v12, v188, v189
	v_cvt_pk_bf16_f32 v13, v190, v191
	global_store_dwordx2 v2, v[12:13], s[24:25] offset:224
	global_load_dwordx4 v[128:131], v1, s[28:29]
	global_load_dwordx4 v[132:135], v1, s[28:29] offset:16
	global_load_dwordx4 v[136:139], v1, s[28:29] offset:32
	global_load_dwordx4 v[140:143], v1, s[28:29] offset:48
	global_load_dwordx2 v[144:145], v2, s[28:29]
	global_load_dwordx2 v[146:147], v2, s[28:29] offset:32
	global_load_dwordx2 v[148:149], v2, s[28:29] offset:64
	global_load_dwordx2 v[150:151], v2, s[28:29] offset:96
	global_load_dwordx2 v[152:153], v2, s[28:29] offset:128
	global_load_dwordx2 v[154:155], v2, s[28:29] offset:160
	global_load_dwordx2 v[156:157], v2, s[28:29] offset:192
	global_load_dwordx2 v[158:159], v2, s[28:29] offset:224
	s_waitcnt vmcnt(28)
	v_lshlrev_b32_e32 v160, 16, v96
	v_and_b32_e32 v161, 0xffff0000, v96
	v_lshlrev_b32_e32 v162, 16, v97
	v_and_b32_e32 v163, 0xffff0000, v97
	v_lshlrev_b32_e32 v164, 16, v98
	v_and_b32_e32 v165, 0xffff0000, v98
	v_lshlrev_b32_e32 v166, 16, v99
	v_and_b32_e32 v167, 0xffff0000, v99
	v_lshlrev_b32_e32 v168, 16, v100
	v_and_b32_e32 v169, 0xffff0000, v100
	v_lshlrev_b32_e32 v170, 16, v101
	v_and_b32_e32 v171, 0xffff0000, v101
	v_lshlrev_b32_e32 v172, 16, v102
	v_and_b32_e32 v173, 0xffff0000, v102
	v_lshlrev_b32_e32 v174, 16, v103
	v_and_b32_e32 v175, 0xffff0000, v103
	v_lshlrev_b32_e32 v176, 16, v104
	v_and_b32_e32 v177, 0xffff0000, v104
	v_lshlrev_b32_e32 v178, 16, v105
	v_and_b32_e32 v179, 0xffff0000, v105
	v_lshlrev_b32_e32 v180, 16, v106
	v_and_b32_e32 v181, 0xffff0000, v106
	v_lshlrev_b32_e32 v182, 16, v107
	v_and_b32_e32 v183, 0xffff0000, v107
	v_lshlrev_b32_e32 v184, 16, v108
	v_and_b32_e32 v185, 0xffff0000, v108
	v_lshlrev_b32_e32 v186, 16, v109
	v_and_b32_e32 v187, 0xffff0000, v109
	v_lshlrev_b32_e32 v188, 16, v110
	v_and_b32_e32 v189, 0xffff0000, v110
	v_lshlrev_b32_e32 v190, 16, v111
	v_and_b32_e32 v191, 0xffff0000, v111
	v_add_f32_e32 v8, v160, v164
	v_add_f32_e32 v9, v161, v165
	v_add_f32_e32 v10, v162, v166
	v_add_f32_e32 v11, v163, v167
	v_add_f32_e32 v8, v8, v168
	v_add_f32_e32 v9, v9, v169
	v_add_f32_e32 v10, v10, v170
	v_add_f32_e32 v11, v11, v171
	v_add_f32_e32 v8, v8, v172
	v_add_f32_e32 v9, v9, v173
	v_add_f32_e32 v10, v10, v174
	v_add_f32_e32 v11, v11, v175
	v_add_f32_e32 v8, v8, v176
	v_add_f32_e32 v9, v9, v177
	v_add_f32_e32 v10, v10, v178
	v_add_f32_e32 v11, v11, v179
	v_add_f32_e32 v8, v8, v180
	v_add_f32_e32 v9, v9, v181
	v_add_f32_e32 v10, v10, v182
	v_add_f32_e32 v11, v11, v183
	v_add_f32_e32 v8, v8, v184
	v_add_f32_e32 v9, v9, v185
	v_add_f32_e32 v10, v10, v186
	v_add_f32_e32 v11, v11, v187
	v_add_f32_e32 v8, v8, v188
	v_add_f32_e32 v9, v9, v189
	v_add_f32_e32 v10, v10, v190
	v_add_f32_e32 v11, v11, v191
	v_add_f32_e32 v8, v8, v9
	v_add_f32_e32 v10, v10, v11
	v_add_f32_e32 v8, v8, v10
	s_nop 1
	v_add_f32_dpp v8, v8, v8 quad_perm:[1,0,3,2] row_mask:0xf bank_mask:0xf
	s_nop 1
	v_add_f32_dpp v8, v8, v8 quad_perm:[2,3,0,1] row_mask:0xf bank_mask:0xf
	v_mul_f32_e32 v8, 0xbc000000, v8
	v_add_f32_e32 v160, v160, v8
	v_add_f32_e32 v161, v161, v8
	v_add_f32_e32 v162, v162, v8
	v_add_f32_e32 v163, v163, v8
	v_add_f32_e32 v164, v164, v8
	v_add_f32_e32 v165, v165, v8
	v_add_f32_e32 v166, v166, v8
	v_add_f32_e32 v167, v167, v8
	v_add_f32_e32 v168, v168, v8
	v_add_f32_e32 v169, v169, v8
	v_add_f32_e32 v170, v170, v8
	v_add_f32_e32 v171, v171, v8
	v_add_f32_e32 v172, v172, v8
	v_add_f32_e32 v173, v173, v8
	v_add_f32_e32 v174, v174, v8
	v_add_f32_e32 v175, v175, v8
	v_add_f32_e32 v176, v176, v8
	v_add_f32_e32 v177, v177, v8
	v_add_f32_e32 v178, v178, v8
	v_add_f32_e32 v179, v179, v8
	v_add_f32_e32 v180, v180, v8
	v_add_f32_e32 v181, v181, v8
	v_add_f32_e32 v182, v182, v8
	v_add_f32_e32 v183, v183, v8
	v_add_f32_e32 v184, v184, v8
	v_add_f32_e32 v185, v185, v8
	v_add_f32_e32 v186, v186, v8
	v_add_f32_e32 v187, v187, v8
	v_add_f32_e32 v188, v188, v8
	v_add_f32_e32 v189, v189, v8
	v_add_f32_e32 v190, v190, v8
	v_add_f32_e32 v191, v191, v8
	v_mul_f32_e32 v8, v160, v160
	v_mul_f32_e32 v9, v161, v161
	v_mul_f32_e32 v10, v162, v162
	v_mul_f32_e32 v11, v163, v163
	v_fmac_f32_e32 v8, v164, v164
	v_fmac_f32_e32 v9, v165, v165
	v_fmac_f32_e32 v10, v166, v166
	v_fmac_f32_e32 v11, v167, v167
	v_fmac_f32_e32 v8, v168, v168
	v_fmac_f32_e32 v9, v169, v169
	v_fmac_f32_e32 v10, v170, v170
	v_fmac_f32_e32 v11, v171, v171
	v_fmac_f32_e32 v8, v172, v172
	v_fmac_f32_e32 v9, v173, v173
	v_fmac_f32_e32 v10, v174, v174
	v_fmac_f32_e32 v11, v175, v175
	v_fmac_f32_e32 v8, v176, v176
; #define LAS __attribute__((address_space(3)))
; __device__ __forceinline__ unsigned f2bf(float f) { unsigned u = __builtin_bit_cast(unsigned, f); return (u + 0x7fffu + ((u >> 16) & 1u)) >> 16; }
; __device__ __forceinline__ unsigned pk2(float lo, float hi) { return pg8::cvt_pk_bf16(lo, hi); }
; __device__ __forceinline__ void gmlp_unit(LAS unsigned char* lds, bf16_t* Z, const float* ln_g, const float* ln_b, const float* b_s, const u32x2 (&uu)[8], const f32x4 (&wreg)[8], const u32x4 (&raw)[4], int cidx, int g, int tid) {
;     ...
;         const float mean = s * (1.f / 128.f); float q2 = 0.f;
; #pragma unroll
;         for (int c = 0; c < 32; ++c) { x[c] -= mean; q2 += x[c] * x[c]; }
;         q2 += __shfl_xor(q2, 1); q2 += __shfl_xor(q2, 2);
;         const float rstd = __builtin_amdgcn_rsqf(q2 * (1.f / 128.f) + EPS);
;         const float* gp = ln_g + g * 128 + cq; const float* bp = ln_b + g * 128 + cq;
; #pragma unroll
;         for (int c4 = 0; c4 < 8; ++c4) { const f32x4 gg = *(const f32x4*)(gp + 4 * c4), bb = *(const f32x4*)(bp + 4 * c4);
; #pragma unroll
;             for (int e = 0; e < 4; ++e) { const int c = 4 * c4 + e; const float y = x[c] * rstd * gg[e] + bb[e];
;                 *(LAS unsigned short*)(VT + (cq + c) * LSTR + j * 2) = (unsigned short)f2bf(y); } }
;     }
;     {
;         const int i = tid >> 2, jq = (tid & 3) * 32;
; #pragma unroll
;         for (int q = 0; q < 4; ++q) { f32x4 a = wreg[2 * q], b = wreg[2 * q + 1];
;             const int j0 = jq + 8 * q;
; #pragma unroll
;             for (int e = 0; e < 4; ++e) { if (j0 + e > i) a[e] = 0.f; if (j0 + 4 + e > i) b[e] = 0.f; }
;             u32x4 w; w.x = pk2(a[0], a[1]); w.y = pk2(a[2], a[3]); w.z = pk2(b[0], b[1]); w.w = pk2(b[2], b[3]);
;             *(LAS u32x4*)(WS + i * LSTR + j0 * 2) = w; }
;     }
;     __syncthreads();
	v_fmac_f32_e32 v9, v177, v177
	v_fmac_f32_e32 v10, v178, v178
	v_fmac_f32_e32 v11, v179, v179
	v_fmac_f32_e32 v8, v180, v180
	v_fmac_f32_e32 v9, v181, v181
	v_fmac_f32_e32 v10, v182, v182
	v_fmac_f32_e32 v11, v183, v183
	v_fmac_f32_e32 v8, v184, v184
	v_fmac_f32_e32 v9, v185, v185
	v_fmac_f32_e32 v10, v186, v186
	v_fmac_f32_e32 v11, v187, v187
	v_fmac_f32_e32 v8, v188, v188
	v_fmac_f32_e32 v9, v189, v189
	v_fmac_f32_e32 v10, v190, v190
	v_fmac_f32_e32 v11, v191, v191
	v_add_f32_e32 v8, v8, v9
	v_add_f32_e32 v10, v10, v11
	v_add_f32_e32 v8, v8, v10
	s_nop 1
	v_add_f32_dpp v8, v8, v8 quad_perm:[1,0,3,2] row_mask:0xf bank_mask:0xf
	s_nop 1
	v_add_f32_dpp v8, v8, v8 quad_perm:[2,3,0,1] row_mask:0xf bank_mask:0xf
	v_fmamk_f32 v8, v8, 0x3c000000, v219
	v_rsq_f32_e32 v8, v8
	s_nop 0
	v_mul_f32_e32 v160, v160, v8
	v_fma_f32 v160, v16, v160, v48
	v_bfe_u32 v9, v160, 16, 1
	v_add3_u32 v160, v160, v9, s81
	ds_write_b16_d16_hi v3, v160
	v_mul_f32_e32 v161, v161, v8
	v_fma_f32 v161, v17, v161, v49
	v_bfe_u32 v10, v161, 16, 1
	v_add3_u32 v161, v161, v10, s81
	ds_write_b16_d16_hi v3, v161 offset:272
	v_mul_f32_e32 v162, v162, v8
	v_fma_f32 v162, v18, v162, v50
	v_bfe_u32 v9, v162, 16, 1
	v_add3_u32 v162, v162, v9, s81
	ds_write_b16_d16_hi v3, v162 offset:544
	v_mul_f32_e32 v163, v163, v8
	v_fma_f32 v163, v19, v163, v51
	v_bfe_u32 v10, v163, 16, 1
	v_add3_u32 v163, v163, v10, s81
	ds_write_b16_d16_hi v3, v163 offset:816
	v_mul_f32_e32 v164, v164, v8
	v_fma_f32 v164, v20, v164, v52
	v_bfe_u32 v9, v164, 16, 1
	v_add3_u32 v164, v164, v9, s81
	ds_write_b16_d16_hi v3, v164 offset:1088
	v_mul_f32_e32 v165, v165, v8
	v_fma_f32 v165, v21, v165, v53
	v_bfe_u32 v10, v165, 16, 1
	v_add3_u32 v165, v165, v10, s81
	ds_write_b16_d16_hi v3, v165 offset:1360
	v_mul_f32_e32 v166, v166, v8
	v_fma_f32 v166, v22, v166, v54
	v_bfe_u32 v9, v166, 16, 1
	v_add3_u32 v166, v166, v9, s81
	ds_write_b16_d16_hi v3, v166 offset:1632
	v_mul_f32_e32 v167, v167, v8
	v_fma_f32 v167, v23, v167, v55
	v_bfe_u32 v10, v167, 16, 1
	v_add3_u32 v167, v167, v10, s81
	ds_write_b16_d16_hi v3, v167 offset:1904
	v_mul_f32_e32 v168, v168, v8
	v_fma_f32 v168, v24, v168, v56
	v_bfe_u32 v9, v168, 16, 1
	v_add3_u32 v168, v168, v9, s81
	ds_write_b16_d16_hi v3, v168 offset:2176
	v_mul_f32_e32 v169, v169, v8
	v_fma_f32 v169, v25, v169, v57
	v_bfe_u32 v10, v169, 16, 1
	v_add3_u32 v169, v169, v10, s81
	ds_write_b16_d16_hi v3, v169 offset:2448
	v_mul_f32_e32 v170, v170, v8
	v_fma_f32 v170, v26, v170, v58
	v_bfe_u32 v9, v170, 16, 1
	v_add3_u32 v170, v170, v9, s81
	ds_write_b16_d16_hi v3, v170 offset:2720
	v_mul_f32_e32 v171, v171, v8
	v_fma_f32 v171, v27, v171, v59
	v_bfe_u32 v10, v171, 16, 1
	v_add3_u32 v171, v171, v10, s81
	ds_write_b16_d16_hi v3, v171 offset:2992
	v_mul_f32_e32 v172, v172, v8
	v_fma_f32 v172, v28, v172, v60
	v_bfe_u32 v9, v172, 16, 1
	v_add3_u32 v172, v172, v9, s81
	ds_write_b16_d16_hi v3, v172 offset:3264
	v_mul_f32_e32 v173, v173, v8
	v_fma_f32 v173, v29, v173, v61
	v_bfe_u32 v10, v173, 16, 1
	v_add3_u32 v173, v173, v10, s81
	ds_write_b16_d16_hi v3, v173 offset:3536
	v_mul_f32_e32 v174, v174, v8
	v_fma_f32 v174, v30, v174, v62
	v_bfe_u32 v9, v174, 16, 1
	v_add3_u32 v174, v174, v9, s81
	ds_write_b16_d16_hi v3, v174 offset:3808
	v_mul_f32_e32 v175, v175, v8
	v_fma_f32 v175, v31, v175, v63
	v_bfe_u32 v10, v175, 16, 1
	v_add3_u32 v175, v175, v10, s81
	ds_write_b16_d16_hi v3, v175 offset:4080
	v_mul_f32_e32 v176, v176, v8
	v_fma_f32 v176, v32, v176, v64
	v_bfe_u32 v9, v176, 16, 1
	v_add3_u32 v176, v176, v9, s81
	ds_write_b16_d16_hi v3, v176 offset:4352
	v_mul_f32_e32 v177, v177, v8
	v_fma_f32 v177, v33, v177, v65
	v_bfe_u32 v10, v177, 16, 1
	v_add3_u32 v177, v177, v10, s81
	ds_write_b16_d16_hi v3, v177 offset:4624
	v_mul_f32_e32 v178, v178, v8
	v_fma_f32 v178, v34, v178, v66
	v_bfe_u32 v9, v178, 16, 1
	v_add3_u32 v178, v178, v9, s81
	ds_write_b16_d16_hi v3, v178 offset:4896
	v_mul_f32_e32 v179, v179, v8
	v_fma_f32 v179, v35, v179, v67
	v_bfe_u32 v10, v179, 16, 1
	v_add3_u32 v179, v179, v10, s81
	ds_write_b16_d16_hi v3, v179 offset:5168
	v_mul_f32_e32 v180, v180, v8
	v_fma_f32 v180, v36, v180, v68
	v_bfe_u32 v9, v180, 16, 1
	v_add3_u32 v180, v180, v9, s81
	ds_write_b16_d16_hi v3, v180 offset:5440
	v_mul_f32_e32 v181, v181, v8
	v_fma_f32 v181, v37, v181, v69
	v_bfe_u32 v10, v181, 16, 1
	v_add3_u32 v181, v181, v10, s81
	ds_write_b16_d16_hi v3, v181 offset:5712
	v_mul_f32_e32 v182, v182, v8
	v_fma_f32 v182, v38, v182, v70
	v_bfe_u32 v9, v182, 16, 1
	v_add3_u32 v182, v182, v9, s81
	ds_write_b16_d16_hi v3, v182 offset:5984
	v_mul_f32_e32 v183, v183, v8
	v_fma_f32 v183, v39, v183, v71
	v_bfe_u32 v10, v183, 16, 1
	v_add3_u32 v183, v183, v10, s81
	ds_write_b16_d16_hi v3, v183 offset:6256
	v_mul_f32_e32 v184, v184, v8
	v_fma_f32 v184, v40, v184, v72
	v_bfe_u32 v9, v184, 16, 1
	v_add3_u32 v184, v184, v9, s81
	ds_write_b16_d16_hi v3, v184 offset:6528
	v_mul_f32_e32 v185, v185, v8
	v_fma_f32 v185, v41, v185, v73
	v_bfe_u32 v10, v185, 16, 1
	v_add3_u32 v185, v185, v10, s81
	ds_write_b16_d16_hi v3, v185 offset:6800
	v_mul_f32_e32 v186, v186, v8
	v_fma_f32 v186, v42, v186, v74
	v_bfe_u32 v9, v186, 16, 1
	v_add3_u32 v186, v186, v9, s81
	ds_write_b16_d16_hi v3, v186 offset:7072
	v_mul_f32_e32 v187, v187, v8
	v_fma_f32 v187, v43, v187, v75
	v_bfe_u32 v10, v187, 16, 1
	v_add3_u32 v187, v187, v10, s81
	ds_write_b16_d16_hi v3, v187 offset:7344
	v_mul_f32_e32 v188, v188, v8
	v_fma_f32 v188, v44, v188, v76
	v_bfe_u32 v9, v188, 16, 1
	v_add3_u32 v188, v188, v9, s81
	ds_write_b16_d16_hi v3, v188 offset:7616
	v_mul_f32_e32 v189, v189, v8
	v_fma_f32 v189, v45, v189, v77
	v_bfe_u32 v10, v189, 16, 1
	v_add3_u32 v189, v189, v10, s81
	ds_write_b16_d16_hi v3, v189 offset:7888
	v_mul_f32_e32 v190, v190, v8
	v_fma_f32 v190, v46, v190, v78
	v_bfe_u32 v9, v190, 16, 1
	v_add3_u32 v190, v190, v9, s81
	ds_write_b16_d16_hi v3, v190 offset:8160
	v_mul_f32_e32 v191, v191, v8
	v_fma_f32 v191, v47, v191, v79
	v_bfe_u32 v10, v191, 16, 1
	v_add3_u32 v191, v191, v10, s81
	ds_write_b16_d16_hi v3, v191 offset:8432
	s_waitcnt lgkmcnt(0)
	s_barrier
; #define LAS __attribute__((address_space(3)))
; __device__ __forceinline__ void gmlp_unit(LAS unsigned char* lds, bf16_t* Z, const float* ln_g, const float* ln_b, const float* b_s, const u32x2 (&uu)[8], const f32x4 (&wreg)[8], const u32x4 (&raw)[4], int cidx, int g, int tid) {
;     ...
;     const int wv = tid >> 6, lane = tid & 63, fr = lane & 15, fq = lane >> 4;
;     f32x4 acc[8];
; #pragma unroll
;     for (int ct = 0; ct < 8; ++ct) acc[ct] = (f32x4){0.f, 0.f, 0.f, 0.f};
; #pragma unroll
;     for (int ks = 0; ks < 4; ++ks) {
;         const bf16x8 bw = *(const LAS bf16x8*)(WS + (wv * 16 + fr) * LSTR + (ks * 32 + fq * 8) * 2);
; #pragma unroll
;         for (int ct = 0; ct < 8; ++ct) { const bf16x8 av = *(const LAS bf16x8*)(VT + (ct * 16 + fr) * LSTR + (ks * 32 + fq * 8) * 2);
;             acc[ct] = __builtin_amdgcn_mfma_f32_16x16x32_bf16(av, bw, acc[ct], 0, 0, 0); }
;     }
	ds_read_b128 v[200:203], v4
	ds_read_b128 v[204:207], v4 offset:4352
	ds_read_b128 v[208:211], v4 offset:8768
	ds_read_b128 v[212:215], v4 offset:13120
	ds_read_b128 v[224:227], v4 offset:17536
	ds_read_b128 v[228:231], v4 offset:21888
	ds_read_b128 v[232:235], v4 offset:26304
	ds_read_b128 v[236:239], v4 offset:30656
	s_waitcnt lgkmcnt(7)
	v_mfma_f32_16x16x32_bf16 v[160:163], v[200:203], v[80:83], 0
	ds_read_b128 v[200:203], v4 offset:64
	s_waitcnt lgkmcnt(7)
	v_mfma_f32_16x16x32_bf16 v[164:167], v[204:207], v[80:83], 0
	ds_read_b128 v[204:207], v4 offset:4416
	s_waitcnt lgkmcnt(7)
	v_mfma_f32_16x16x32_bf16 v[168:171], v[208:211], v[80:83], 0
	ds_read_b128 v[208:211], v4 offset:8704
	s_waitcnt lgkmcnt(7)
	v_mfma_f32_16x16x32_bf16 v[172:175], v[212:215], v[80:83], 0
	ds_read_b128 v[212:215], v4 offset:13056
	s_waitcnt lgkmcnt(7)
	v_mfma_f32_16x16x32_bf16 v[176:179], v[224:227], v[80:83], 0
	ds_read_b128 v[224:227], v4 offset:17600
	s_waitcnt lgkmcnt(7)
	v_mfma_f32_16x16x32_bf16 v[180:183], v[228:231], v[80:83], 0
	ds_read_b128 v[228:231], v4 offset:21952
	s_waitcnt lgkmcnt(7)
	v_mfma_f32_16x16x32_bf16 v[184:187], v[232:235], v[80:83], 0
	ds_read_b128 v[232:235], v4 offset:26240
	s_waitcnt lgkmcnt(7)
	v_mfma_f32_16x16x32_bf16 v[188:191], v[236:239], v[80:83], 0
	ds_read_b128 v[236:239], v4 offset:30592
	s_waitcnt lgkmcnt(7)
	v_mfma_f32_16x16x32_bf16 v[160:163], v[200:203], v[84:87], v[160:163]
	ds_read_b128 v[200:203], v4 offset:128
	s_waitcnt lgkmcnt(7)
	v_mfma_f32_16x16x32_bf16 v[164:167], v[204:207], v[84:87], v[164:167]
	ds_read_b128 v[204:207], v4 offset:4480
	s_waitcnt lgkmcnt(7)
	v_mfma_f32_16x16x32_bf16 v[168:171], v[208:211], v[84:87], v[168:171]
	ds_read_b128 v[208:211], v4 offset:8896
	s_waitcnt lgkmcnt(7)
	v_mfma_f32_16x16x32_bf16 v[172:175], v[212:215], v[84:87], v[172:175]
	ds_read_b128 v[212:215], v4 offset:13248
	s_waitcnt lgkmcnt(7)
	v_mfma_f32_16x16x32_bf16 v[176:179], v[224:227], v[84:87], v[176:179]
	ds_read_b128 v[224:227], v4 offset:17408
	s_waitcnt lgkmcnt(7)
	v_mfma_f32_16x16x32_bf16 v[180:183], v[228:231], v[84:87], v[180:183]
	ds_read_b128 v[228:231], v4 offset:21760
	s_waitcnt lgkmcnt(7)
	v_mfma_f32_16x16x32_bf16 v[184:187], v[232:235], v[84:87], v[184:187]
	ds_read_b128 v[232:235], v4 offset:26176
	s_waitcnt lgkmcnt(7)
	v_mfma_f32_16x16x32_bf16 v[188:191], v[236:239], v[84:87], v[188:191]
	ds_read_b128 v[236:239], v4 offset:30528
	s_waitcnt lgkmcnt(7)
	v_mfma_f32_16x16x32_bf16 v[160:163], v[200:203], v[88:91], v[160:163]
	ds_read_b128 v[200:203], v4 offset:192
	s_waitcnt lgkmcnt(7)
	v_mfma_f32_16x16x32_bf16 v[164:167], v[204:207], v[88:91], v[164:167]
	ds_read_b128 v[204:207], v4 offset:4544
	s_waitcnt lgkmcnt(7)
	v_mfma_f32_16x16x32_bf16 v[168:171], v[208:211], v[88:91], v[168:171]
	ds_read_b128 v[208:211], v4 offset:8832
	s_waitcnt lgkmcnt(7)
	v_mfma_f32_16x16x32_bf16 v[172:175], v[212:215], v[88:91], v[172:175]
	ds_read_b128 v[212:215], v4 offset:13184
	s_waitcnt lgkmcnt(7)
	v_mfma_f32_16x16x32_bf16 v[176:179], v[224:227], v[88:91], v[176:179]
	ds_read_b128 v[224:227], v4 offset:17472
	s_waitcnt lgkmcnt(7)
	v_mfma_f32_16x16x32_bf16 v[180:183], v[228:231], v[88:91], v[180:183]
	ds_read_b128 v[228:231], v4 offset:21824
	s_waitcnt lgkmcnt(7)
	v_mfma_f32_16x16x32_bf16 v[184:187], v[232:235], v[88:91], v[184:187]
	ds_read_b128 v[232:235], v4 offset:26112
	s_waitcnt lgkmcnt(7)
	v_mfma_f32_16x16x32_bf16 v[188:191], v[236:239], v[88:91], v[188:191]
	ds_read_b128 v[236:239], v4 offset:30464
	s_waitcnt lgkmcnt(7)
	v_mfma_f32_16x16x32_bf16 v[160:163], v[200:203], v[92:95], v[160:163]
	s_waitcnt lgkmcnt(6)
	v_mfma_f32_16x16x32_bf16 v[164:167], v[204:207], v[92:95], v[164:167]
	s_waitcnt lgkmcnt(5)
	v_mfma_f32_16x16x32_bf16 v[168:171], v[208:211], v[92:95], v[168:171]
	s_waitcnt lgkmcnt(4)
	v_mfma_f32_16x16x32_bf16 v[172:175], v[212:215], v[92:95], v[172:175]
	s_waitcnt lgkmcnt(3)
	v_mfma_f32_16x16x32_bf16 v[176:179], v[224:227], v[92:95], v[176:179]
	s_waitcnt lgkmcnt(2)
	v_mfma_f32_16x16x32_bf16 v[180:183], v[228:231], v[92:95], v[180:183]
	s_waitcnt lgkmcnt(1)
	v_mfma_f32_16x16x32_bf16 v[184:187], v[232:235], v[92:95], v[184:187]
	s_waitcnt lgkmcnt(0)
	v_mfma_f32_16x16x32_bf16 v[188:191], v[236:239], v[92:95], v[188:191]
	s_waitcnt vmcnt(20)
; __device__ __forceinline__ unsigned pk2(float lo, float hi) { return pg8::cvt_pk_bf16(lo, hi); }
; __device__ __forceinline__ void gmlp_unit(LAS unsigned char* lds, bf16_t* Z, const float* ln_g, const float* ln_b, const float* b_s, const u32x2 (&uu)[8], const f32x4 (&wreg)[8], const u32x4 (&raw)[4], int cidx, int g, int tid) {
;     ...
;         const int j = tid >> 2, cq = (tid & 3) * 32;
;         float x[32];
; #pragma unroll
;         for (int q = 0; q < 4; ++q)
; #pragma unroll
;             for (int e = 0; e < 4; ++e) { x[8 * q + 2 * e] = bf_lo(raw[q][e]); x[8 * q + 2 * e + 1] = bf_hi(raw[q][e]); }
;         float s = 0.f;
; #pragma unroll
;         for (int c = 0; c < 32; ++c) s += x[c];
;         s += __shfl_xor(s, 1); s += __shfl_xor(s, 2);
;     ...
;     {
;         const int i = wv * 16 + fr; const float bs = b_s[g * 128 + i];
;         bf16_t* up = Z + (size_t)(row0 + i) * INW + g * 128 + 4 * fq;
; #pragma unroll
;         for (int ct = 0; ct < 8; ++ct) {
;             u32x2 w; w.x = pk2(bf_lo(uu[ct].x) * (acc[ct][0] + bs), bf_hi(uu[ct].x) * (acc[ct][1] + bs)); w.y = pk2(bf_lo(uu[ct].y) * (acc[ct][2] + bs), bf_hi(uu[ct].y) * (acc[ct][3] + bs));
;             *(u32x2*)(up + 16 * ct) = w; }
;     }
	v_add_f32_e32 v160, v160, v7
	v_add_f32_e32 v161, v161, v7
	v_add_f32_e32 v162, v162, v7
	v_add_f32_e32 v163, v163, v7
	v_lshlrev_b32_e32 v8, 16, v112
	v_and_b32_e32 v9, 0xffff0000, v112
	v_lshlrev_b32_e32 v10, 16, v113
	v_and_b32_e32 v11, 0xffff0000, v113
	v_mul_f32_e32 v160, v8, v160
	v_mul_f32_e32 v161, v9, v161
	v_mul_f32_e32 v162, v10, v162
	v_mul_f32_e32 v163, v11, v163
	v_cvt_pk_bf16_f32 v12, v160, v161
	v_cvt_pk_bf16_f32 v13, v162, v163
	global_store_dwordx2 v2, v[12:13], s[26:27]
	s_nop 0
	v_add_f32_e32 v164, v164, v7
	v_add_f32_e32 v165, v165, v7
	v_add_f32_e32 v166, v166, v7
	v_add_f32_e32 v167, v167, v7
	v_lshlrev_b32_e32 v8, 16, v114
	v_and_b32_e32 v9, 0xffff0000, v114
	v_lshlrev_b32_e32 v10, 16, v115
	v_and_b32_e32 v11, 0xffff0000, v115
	v_mul_f32_e32 v164, v8, v164
	v_mul_f32_e32 v165, v9, v165
	v_mul_f32_e32 v166, v10, v166
	v_mul_f32_e32 v167, v11, v167
	v_cvt_pk_bf16_f32 v12, v164, v165
	v_cvt_pk_bf16_f32 v13, v166, v167
	global_store_dwordx2 v2, v[12:13], s[26:27] offset:32
	s_nop 0
	v_add_f32_e32 v168, v168, v7
	v_add_f32_e32 v169, v169, v7
	v_add_f32_e32 v170, v170, v7
	v_add_f32_e32 v171, v171, v7
	v_lshlrev_b32_e32 v8, 16, v116
	v_and_b32_e32 v9, 0xffff0000, v116
	v_lshlrev_b32_e32 v10, 16, v117
	v_and_b32_e32 v11, 0xffff0000, v117
	v_mul_f32_e32 v168, v8, v168
	v_mul_f32_e32 v169, v9, v169
	v_mul_f32_e32 v170, v10, v170
	v_mul_f32_e32 v171, v11, v171
	v_cvt_pk_bf16_f32 v12, v168, v169
	v_cvt_pk_bf16_f32 v13, v170, v171
	global_store_dwordx2 v2, v[12:13], s[26:27] offset:64
	s_nop 0
	v_add_f32_e32 v172, v172, v7
	v_add_f32_e32 v173, v173, v7
	v_add_f32_e32 v174, v174, v7
	v_add_f32_e32 v175, v175, v7
	v_lshlrev_b32_e32 v8, 16, v118
	v_and_b32_e32 v9, 0xffff0000, v118
	v_lshlrev_b32_e32 v10, 16, v119
	v_and_b32_e32 v11, 0xffff0000, v119
	v_mul_f32_e32 v172, v8, v172
	v_mul_f32_e32 v173, v9, v173
	v_mul_f32_e32 v174, v10, v174
	v_mul_f32_e32 v175, v11, v175
	v_cvt_pk_bf16_f32 v12, v172, v173
	v_cvt_pk_bf16_f32 v13, v174, v175
	global_store_dwordx2 v2, v[12:13], s[26:27] offset:96
	s_nop 0
	v_add_f32_e32 v176, v176, v7
	v_add_f32_e32 v177, v177, v7
	v_add_f32_e32 v178, v178, v7
	v_add_f32_e32 v179, v179, v7
	v_lshlrev_b32_e32 v8, 16, v120
	v_and_b32_e32 v9, 0xffff0000, v120
	v_lshlrev_b32_e32 v10, 16, v121
	v_and_b32_e32 v11, 0xffff0000, v121
	v_mul_f32_e32 v176, v8, v176
	v_mul_f32_e32 v177, v9, v177
	v_mul_f32_e32 v178, v10, v178
	v_mul_f32_e32 v179, v11, v179
	v_cvt_pk_bf16_f32 v12, v176, v177
	v_cvt_pk_bf16_f32 v13, v178, v179
	global_store_dwordx2 v2, v[12:13], s[26:27] offset:128
	s_nop 0
	v_add_f32_e32 v180, v180, v7
	v_add_f32_e32 v181, v181, v7
	v_add_f32_e32 v182, v182, v7
	v_add_f32_e32 v183, v183, v7
	v_lshlrev_b32_e32 v8, 16, v122
	v_and_b32_e32 v9, 0xffff0000, v122
	v_lshlrev_b32_e32 v10, 16, v123
	v_and_b32_e32 v11, 0xffff0000, v123
	v_mul_f32_e32 v180, v8, v180
	v_mul_f32_e32 v181, v9, v181
	v_mul_f32_e32 v182, v10, v182
	v_mul_f32_e32 v183, v11, v183
	v_cvt_pk_bf16_f32 v12, v180, v181
	v_cvt_pk_bf16_f32 v13, v182, v183
	global_store_dwordx2 v2, v[12:13], s[26:27] offset:160
	s_nop 0
	v_add_f32_e32 v184, v184, v7
	v_add_f32_e32 v185, v185, v7
	v_add_f32_e32 v186, v186, v7
	v_add_f32_e32 v187, v187, v7
	v_lshlrev_b32_e32 v8, 16, v124
	v_and_b32_e32 v9, 0xffff0000, v124
	v_lshlrev_b32_e32 v10, 16, v125
	v_and_b32_e32 v11, 0xffff0000, v125
	v_mul_f32_e32 v184, v8, v184
	v_mul_f32_e32 v185, v9, v185
	v_mul_f32_e32 v186, v10, v186
	v_mul_f32_e32 v187, v11, v187
	v_cvt_pk_bf16_f32 v12, v184, v185
	v_cvt_pk_bf16_f32 v13, v186, v187
	global_store_dwordx2 v2, v[12:13], s[26:27] offset:192
	s_nop 0
	v_add_f32_e32 v188, v188, v7
	v_add_f32_e32 v189, v189, v7
	v_add_f32_e32 v190, v190, v7
	v_add_f32_e32 v191, v191, v7
	v_lshlrev_b32_e32 v8, 16, v126
	v_and_b32_e32 v9, 0xffff0000, v126
	v_lshlrev_b32_e32 v10, 16, v127
	v_and_b32_e32 v11, 0xffff0000, v127
	v_mul_f32_e32 v188, v8, v188
	v_mul_f32_e32 v189, v9, v189
	v_mul_f32_e32 v190, v10, v190
	v_mul_f32_e32 v191, v11, v191
	v_cvt_pk_bf16_f32 v12, v188, v189
	v_cvt_pk_bf16_f32 v13, v190, v191
	global_store_dwordx2 v2, v[12:13], s[26:27] offset:224
	s_waitcnt vmcnt(16)
	v_lshlrev_b32_e32 v160, 16, v128
	v_and_b32_e32 v161, 0xffff0000, v128
	v_lshlrev_b32_e32 v162, 16, v129
	v_and_b32_e32 v163, 0xffff0000, v129
	v_lshlrev_b32_e32 v164, 16, v130
	v_and_b32_e32 v165, 0xffff0000, v130
	v_lshlrev_b32_e32 v166, 16, v131
	v_and_b32_e32 v167, 0xffff0000, v131
	v_lshlrev_b32_e32 v168, 16, v132
	v_and_b32_e32 v169, 0xffff0000, v132
	v_lshlrev_b32_e32 v170, 16, v133
	v_and_b32_e32 v171, 0xffff0000, v133
	v_lshlrev_b32_e32 v172, 16, v134
	v_and_b32_e32 v173, 0xffff0000, v134
	v_lshlrev_b32_e32 v174, 16, v135
	v_and_b32_e32 v175, 0xffff0000, v135
	v_lshlrev_b32_e32 v176, 16, v136
	v_and_b32_e32 v177, 0xffff0000, v136
	v_lshlrev_b32_e32 v178, 16, v137
	v_and_b32_e32 v179, 0xffff0000, v137
	v_lshlrev_b32_e32 v180, 16, v138
	v_and_b32_e32 v181, 0xffff0000, v138
	v_lshlrev_b32_e32 v182, 16, v139
	v_and_b32_e32 v183, 0xffff0000, v139
	v_lshlrev_b32_e32 v184, 16, v140
	v_and_b32_e32 v185, 0xffff0000, v140
	v_lshlrev_b32_e32 v186, 16, v141
	v_and_b32_e32 v187, 0xffff0000, v141
	v_lshlrev_b32_e32 v188, 16, v142
	v_and_b32_e32 v189, 0xffff0000, v142
	v_lshlrev_b32_e32 v190, 16, v143
	v_and_b32_e32 v191, 0xffff0000, v143
	v_add_f32_e32 v8, v160, v164
	v_add_f32_e32 v9, v161, v165
	v_add_f32_e32 v10, v162, v166
	v_add_f32_e32 v11, v163, v167
	v_add_f32_e32 v8, v8, v168
	v_add_f32_e32 v9, v9, v169
	v_add_f32_e32 v10, v10, v170
	v_add_f32_e32 v11, v11, v171
	v_add_f32_e32 v8, v8, v172
	v_add_f32_e32 v9, v9, v173
	v_add_f32_e32 v10, v10, v174
	v_add_f32_e32 v11, v11, v175
	v_add_f32_e32 v8, v8, v176
; #define LAS __attribute__((address_space(3)))
; __device__ __forceinline__ unsigned f2bf(float f) { unsigned u = __builtin_bit_cast(unsigned, f); return (u + 0x7fffu + ((u >> 16) & 1u)) >> 16; }
; __device__ __forceinline__ void gmlp_unit(LAS unsigned char* lds, bf16_t* Z, const float* ln_g, const float* ln_b, const float* b_s, const u32x2 (&uu)[8], const f32x4 (&wreg)[8], const u32x4 (&raw)[4], int cidx, int g, int tid) {
;     ...
;         float s = 0.f;
; #pragma unroll
;         for (int c = 0; c < 32; ++c) s += x[c];
;         s += __shfl_xor(s, 1); s += __shfl_xor(s, 2);
;         const float mean = s * (1.f / 128.f); float q2 = 0.f;
; #pragma unroll
;         for (int c = 0; c < 32; ++c) { x[c] -= mean; q2 += x[c] * x[c]; }
;         q2 += __shfl_xor(q2, 1); q2 += __shfl_xor(q2, 2);
;         const float rstd = __builtin_amdgcn_rsqf(q2 * (1.f / 128.f) + EPS);
;         const float* gp = ln_g + g * 128 + cq; const float* bp = ln_b + g * 128 + cq;
; #pragma unroll
;         for (int c4 = 0; c4 < 8; ++c4) { const f32x4 gg = *(const f32x4*)(gp + 4 * c4), bb = *(const f32x4*)(bp + 4 * c4);
; #pragma unroll
;             for (int e = 0; e < 4; ++e) { const int c = 4 * c4 + e; const float y = x[c] * rstd * gg[e] + bb[e];
;                 *(LAS unsigned short*)(VT + (cq + c) * LSTR + j * 2) = (unsigned short)f2bf(y); } }
	v_add_f32_e32 v9, v9, v177
	v_add_f32_e32 v10, v10, v178
	v_add_f32_e32 v11, v11, v179
	v_add_f32_e32 v8, v8, v180
	v_add_f32_e32 v9, v9, v181
	v_add_f32_e32 v10, v10, v182
	v_add_f32_e32 v11, v11, v183
	v_add_f32_e32 v8, v8, v184
	v_add_f32_e32 v9, v9, v185
	v_add_f32_e32 v10, v10, v186
	v_add_f32_e32 v11, v11, v187
	v_add_f32_e32 v8, v8, v188
	v_add_f32_e32 v9, v9, v189
	v_add_f32_e32 v10, v10, v190
	v_add_f32_e32 v11, v11, v191
	v_add_f32_e32 v8, v8, v9
	v_add_f32_e32 v10, v10, v11
	v_add_f32_e32 v8, v8, v10
	s_nop 1
	v_add_f32_dpp v8, v8, v8 quad_perm:[1,0,3,2] row_mask:0xf bank_mask:0xf
	s_nop 1
	v_add_f32_dpp v8, v8, v8 quad_perm:[2,3,0,1] row_mask:0xf bank_mask:0xf
	v_mul_f32_e32 v8, 0xbc000000, v8
	v_add_f32_e32 v160, v160, v8
	v_add_f32_e32 v161, v161, v8
	v_add_f32_e32 v162, v162, v8
	v_add_f32_e32 v163, v163, v8
	v_add_f32_e32 v164, v164, v8
	v_add_f32_e32 v165, v165, v8
	v_add_f32_e32 v166, v166, v8
	v_add_f32_e32 v167, v167, v8
	v_add_f32_e32 v168, v168, v8
	v_add_f32_e32 v169, v169, v8
	v_add_f32_e32 v170, v170, v8
	v_add_f32_e32 v171, v171, v8
	v_add_f32_e32 v172, v172, v8
	v_add_f32_e32 v173, v173, v8
	v_add_f32_e32 v174, v174, v8
	v_add_f32_e32 v175, v175, v8
	v_add_f32_e32 v176, v176, v8
	v_add_f32_e32 v177, v177, v8
	v_add_f32_e32 v178, v178, v8
	v_add_f32_e32 v179, v179, v8
	v_add_f32_e32 v180, v180, v8
	v_add_f32_e32 v181, v181, v8
	v_add_f32_e32 v182, v182, v8
	v_add_f32_e32 v183, v183, v8
	v_add_f32_e32 v184, v184, v8
	v_add_f32_e32 v185, v185, v8
	v_add_f32_e32 v186, v186, v8
	v_add_f32_e32 v187, v187, v8
	v_add_f32_e32 v188, v188, v8
	v_add_f32_e32 v189, v189, v8
	v_add_f32_e32 v190, v190, v8
	v_add_f32_e32 v191, v191, v8
	v_mul_f32_e32 v8, v160, v160
	v_mul_f32_e32 v9, v161, v161
	v_mul_f32_e32 v10, v162, v162
	v_mul_f32_e32 v11, v163, v163
	v_fmac_f32_e32 v8, v164, v164
	v_fmac_f32_e32 v9, v165, v165
	v_fmac_f32_e32 v10, v166, v166
	v_fmac_f32_e32 v11, v167, v167
	v_fmac_f32_e32 v8, v168, v168
	v_fmac_f32_e32 v9, v169, v169
	v_fmac_f32_e32 v10, v170, v170
	v_fmac_f32_e32 v11, v171, v171
	v_fmac_f32_e32 v8, v172, v172
	v_fmac_f32_e32 v9, v173, v173
	v_fmac_f32_e32 v10, v174, v174
	v_fmac_f32_e32 v11, v175, v175
	v_fmac_f32_e32 v8, v176, v176
	v_fmac_f32_e32 v9, v177, v177
	v_fmac_f32_e32 v10, v178, v178
	v_fmac_f32_e32 v11, v179, v179
	v_fmac_f32_e32 v8, v180, v180
	v_fmac_f32_e32 v9, v181, v181
	v_fmac_f32_e32 v10, v182, v182
	v_fmac_f32_e32 v11, v183, v183
	v_fmac_f32_e32 v8, v184, v184
	v_fmac_f32_e32 v9, v185, v185
	v_fmac_f32_e32 v10, v186, v186
	v_fmac_f32_e32 v11, v187, v187
	v_fmac_f32_e32 v8, v188, v188
	v_fmac_f32_e32 v9, v189, v189
	v_fmac_f32_e32 v10, v190, v190
	v_fmac_f32_e32 v11, v191, v191
	v_add_f32_e32 v8, v8, v9
	v_add_f32_e32 v10, v10, v11
	v_add_f32_e32 v8, v8, v10
	s_nop 1
	v_add_f32_dpp v8, v8, v8 quad_perm:[1,0,3,2] row_mask:0xf bank_mask:0xf
	s_nop 1
	v_add_f32_dpp v8, v8, v8 quad_perm:[2,3,0,1] row_mask:0xf bank_mask:0xf
	v_fmamk_f32 v8, v8, 0x3c000000, v219
	v_rsq_f32_e32 v8, v8
	s_nop 0
	v_mul_f32_e32 v160, v160, v8
	v_fma_f32 v160, v16, v160, v48
	v_bfe_u32 v9, v160, 16, 1
	v_add3_u32 v160, v160, v9, s81
	ds_write_b16_d16_hi v3, v160 offset:34816
	v_mul_f32_e32 v161, v161, v8
	v_fma_f32 v161, v17, v161, v49
	v_bfe_u32 v10, v161, 16, 1
	v_add3_u32 v161, v161, v10, s81
	ds_write_b16_d16_hi v3, v161 offset:35088
	v_mul_f32_e32 v162, v162, v8
	v_fma_f32 v162, v18, v162, v50
	v_bfe_u32 v9, v162, 16, 1
	v_add3_u32 v162, v162, v9, s81
	ds_write_b16_d16_hi v3, v162 offset:35360
	v_mul_f32_e32 v163, v163, v8
	v_fma_f32 v163, v19, v163, v51
	v_bfe_u32 v10, v163, 16, 1
	v_add3_u32 v163, v163, v10, s81
	ds_write_b16_d16_hi v3, v163 offset:35632
	v_mul_f32_e32 v164, v164, v8
	v_fma_f32 v164, v20, v164, v52
	v_bfe_u32 v9, v164, 16, 1
	v_add3_u32 v164, v164, v9, s81
	ds_write_b16_d16_hi v3, v164 offset:35904
	v_mul_f32_e32 v165, v165, v8
	v_fma_f32 v165, v21, v165, v53
	v_bfe_u32 v10, v165, 16, 1
	v_add3_u32 v165, v165, v10, s81
	ds_write_b16_d16_hi v3, v165 offset:36176
	v_mul_f32_e32 v166, v166, v8
	v_fma_f32 v166, v22, v166, v54
	v_bfe_u32 v9, v166, 16, 1
	v_add3_u32 v166, v166, v9, s81
	ds_write_b16_d16_hi v3, v166 offset:36448
	v_mul_f32_e32 v167, v167, v8
	v_fma_f32 v167, v23, v167, v55
	v_bfe_u32 v10, v167, 16, 1
	v_add3_u32 v167, v167, v10, s81
	ds_write_b16_d16_hi v3, v167 offset:36720
	v_mul_f32_e32 v168, v168, v8
	v_fma_f32 v168, v24, v168, v56
	v_bfe_u32 v9, v168, 16, 1
	v_add3_u32 v168, v168, v9, s81
	ds_write_b16_d16_hi v3, v168 offset:36992
	v_mul_f32_e32 v169, v169, v8
	v_fma_f32 v169, v25, v169, v57
	v_bfe_u32 v10, v169, 16, 1
	v_add3_u32 v169, v169, v10, s81
	ds_write_b16_d16_hi v3, v169 offset:37264
	v_mul_f32_e32 v170, v170, v8
	v_fma_f32 v170, v26, v170, v58
	v_bfe_u32 v9, v170, 16, 1
	v_add3_u32 v170, v170, v9, s81
	ds_write_b16_d16_hi v3, v170 offset:37536
	v_mul_f32_e32 v171, v171, v8
	v_fma_f32 v171, v27, v171, v59
	v_bfe_u32 v10, v171, 16, 1
	v_add3_u32 v171, v171, v10, s81
	ds_write_b16_d16_hi v3, v171 offset:37808
	v_mul_f32_e32 v172, v172, v8
	v_fma_f32 v172, v28, v172, v60
	v_bfe_u32 v9, v172, 16, 1
	v_add3_u32 v172, v172, v9, s81
	ds_write_b16_d16_hi v3, v172 offset:38080
	v_mul_f32_e32 v173, v173, v8
	v_fma_f32 v173, v29, v173, v61
	v_bfe_u32 v10, v173, 16, 1
	v_add3_u32 v173, v173, v10, s81
	ds_write_b16_d16_hi v3, v173 offset:38352
	v_mul_f32_e32 v174, v174, v8
	v_fma_f32 v174, v30, v174, v62
	v_bfe_u32 v9, v174, 16, 1
	v_add3_u32 v174, v174, v9, s81
	ds_write_b16_d16_hi v3, v174 offset:38624
	v_mul_f32_e32 v175, v175, v8
	v_fma_f32 v175, v31, v175, v63
	v_bfe_u32 v10, v175, 16, 1
	v_add3_u32 v175, v175, v10, s81
	ds_write_b16_d16_hi v3, v175 offset:38896
; #define LAS __attribute__((address_space(3)))
; __device__ __forceinline__ unsigned f2bf(float f) { unsigned u = __builtin_bit_cast(unsigned, f); return (u + 0x7fffu + ((u >> 16) & 1u)) >> 16; }
; __device__ __forceinline__ unsigned pk2(float lo, float hi) { return pg8::cvt_pk_bf16(lo, hi); }
; __device__ __forceinline__ void gmlp_unit(LAS unsigned char* lds, bf16_t* Z, const float* ln_g, const float* ln_b, const float* b_s, const u32x2 (&uu)[8], const f32x4 (&wreg)[8], const u32x4 (&raw)[4], int cidx, int g, int tid) {
;     ...
;             for (int e = 0; e < 4; ++e) { const int c = 4 * c4 + e; const float y = x[c] * rstd * gg[e] + bb[e];
;                 *(LAS unsigned short*)(VT + (cq + c) * LSTR + j * 2) = (unsigned short)f2bf(y); } }
;     }
;     {
;         const int i = tid >> 2, jq = (tid & 3) * 32;
; #pragma unroll
;         for (int q = 0; q < 4; ++q) { f32x4 a = wreg[2 * q], b = wreg[2 * q + 1];
;             const int j0 = jq + 8 * q;
; #pragma unroll
;             for (int e = 0; e < 4; ++e) { if (j0 + e > i) a[e] = 0.f; if (j0 + 4 + e > i) b[e] = 0.f; }
;             u32x4 w; w.x = pk2(a[0], a[1]); w.y = pk2(a[2], a[3]); w.z = pk2(b[0], b[1]); w.w = pk2(b[2], b[3]);
;             *(LAS u32x4*)(WS + i * LSTR + j0 * 2) = w; }
;     }
;     __syncthreads();
;     const int wv = tid >> 6, lane = tid & 63, fr = lane & 15, fq = lane >> 4;
;     f32x4 acc[8];
; #pragma unroll
;     for (int ct = 0; ct < 8; ++ct) acc[ct] = (f32x4){0.f, 0.f, 0.f, 0.f};
; #pragma unroll
;     for (int ks = 0; ks < 4; ++ks) {
;         const bf16x8 bw = *(const LAS bf16x8*)(WS + (wv * 16 + fr) * LSTR + (ks * 32 + fq * 8) * 2);
; #pragma unroll
;         for (int ct = 0; ct < 8; ++ct) { const bf16x8 av = *(const LAS bf16x8*)(VT + (ct * 16 + fr) * LSTR + (ks * 32 + fq * 8) * 2);
;             acc[ct] = __builtin_amdgcn_mfma_f32_16x16x32_bf16(av, bw, acc[ct], 0, 0, 0); }
	v_mul_f32_e32 v176, v176, v8
	v_fma_f32 v176, v32, v176, v64
	v_bfe_u32 v9, v176, 16, 1
	v_add3_u32 v176, v176, v9, s81
	ds_write_b16_d16_hi v3, v176 offset:39168
	v_mul_f32_e32 v177, v177, v8
	v_fma_f32 v177, v33, v177, v65
	v_bfe_u32 v10, v177, 16, 1
	v_add3_u32 v177, v177, v10, s81
	ds_write_b16_d16_hi v3, v177 offset:39440
	v_mul_f32_e32 v178, v178, v8
	v_fma_f32 v178, v34, v178, v66
	v_bfe_u32 v9, v178, 16, 1
	v_add3_u32 v178, v178, v9, s81
	ds_write_b16_d16_hi v3, v178 offset:39712
	v_mul_f32_e32 v179, v179, v8
	v_fma_f32 v179, v35, v179, v67
	v_bfe_u32 v10, v179, 16, 1
	v_add3_u32 v179, v179, v10, s81
	ds_write_b16_d16_hi v3, v179 offset:39984
	v_mul_f32_e32 v180, v180, v8
	v_fma_f32 v180, v36, v180, v68
	v_bfe_u32 v9, v180, 16, 1
	v_add3_u32 v180, v180, v9, s81
	ds_write_b16_d16_hi v3, v180 offset:40256
	v_mul_f32_e32 v181, v181, v8
	v_fma_f32 v181, v37, v181, v69
	v_bfe_u32 v10, v181, 16, 1
	v_add3_u32 v181, v181, v10, s81
	ds_write_b16_d16_hi v3, v181 offset:40528
	v_mul_f32_e32 v182, v182, v8
	v_fma_f32 v182, v38, v182, v70
	v_bfe_u32 v9, v182, 16, 1
	v_add3_u32 v182, v182, v9, s81
	ds_write_b16_d16_hi v3, v182 offset:40800
	v_mul_f32_e32 v183, v183, v8
	v_fma_f32 v183, v39, v183, v71
	v_bfe_u32 v10, v183, 16, 1
	v_add3_u32 v183, v183, v10, s81
	ds_write_b16_d16_hi v3, v183 offset:41072
	v_mul_f32_e32 v184, v184, v8
	v_fma_f32 v184, v40, v184, v72
	v_bfe_u32 v9, v184, 16, 1
	v_add3_u32 v184, v184, v9, s81
	ds_write_b16_d16_hi v3, v184 offset:41344
	v_mul_f32_e32 v185, v185, v8
	v_fma_f32 v185, v41, v185, v73
	v_bfe_u32 v10, v185, 16, 1
	v_add3_u32 v185, v185, v10, s81
	ds_write_b16_d16_hi v3, v185 offset:41616
	v_mul_f32_e32 v186, v186, v8
	v_fma_f32 v186, v42, v186, v74
	v_bfe_u32 v9, v186, 16, 1
	v_add3_u32 v186, v186, v9, s81
	ds_write_b16_d16_hi v3, v186 offset:41888
	v_mul_f32_e32 v187, v187, v8
	v_fma_f32 v187, v43, v187, v75
	v_bfe_u32 v10, v187, 16, 1
	v_add3_u32 v187, v187, v10, s81
	ds_write_b16_d16_hi v3, v187 offset:42160
	v_mul_f32_e32 v188, v188, v8
	v_fma_f32 v188, v44, v188, v76
	v_bfe_u32 v9, v188, 16, 1
	v_add3_u32 v188, v188, v9, s81
	ds_write_b16_d16_hi v3, v188 offset:42432
	v_mul_f32_e32 v189, v189, v8
	v_fma_f32 v189, v45, v189, v77
	v_bfe_u32 v10, v189, 16, 1
	v_add3_u32 v189, v189, v10, s81
	ds_write_b16_d16_hi v3, v189 offset:42704
	v_mul_f32_e32 v190, v190, v8
	v_fma_f32 v190, v46, v190, v78
	v_bfe_u32 v9, v190, 16, 1
	v_add3_u32 v190, v190, v9, s81
	ds_write_b16_d16_hi v3, v190 offset:42976
	v_mul_f32_e32 v191, v191, v8
	v_fma_f32 v191, v47, v191, v79
	v_bfe_u32 v10, v191, 16, 1
	v_add3_u32 v191, v191, v10, s81
	ds_write_b16_d16_hi v3, v191 offset:43248
	s_waitcnt lgkmcnt(0)
	s_barrier
	ds_read_b128 v[200:203], v4 offset:34816
	ds_read_b128 v[204:207], v4 offset:39168
	ds_read_b128 v[208:211], v4 offset:43584
	ds_read_b128 v[212:215], v4 offset:47936
	ds_read_b128 v[224:227], v4 offset:52352
	ds_read_b128 v[228:231], v4 offset:56704
	ds_read_b128 v[232:235], v4 offset:61120
	ds_read_b128 v[236:239], v4 offset:65472
	s_waitcnt lgkmcnt(7)
	v_mfma_f32_16x16x32_bf16 v[160:163], v[200:203], v[80:83], 0
	ds_read_b128 v[200:203], v4 offset:34880
	s_waitcnt lgkmcnt(7)
	v_mfma_f32_16x16x32_bf16 v[164:167], v[204:207], v[80:83], 0
	ds_read_b128 v[204:207], v4 offset:39232
	s_waitcnt lgkmcnt(7)
	v_mfma_f32_16x16x32_bf16 v[168:171], v[208:211], v[80:83], 0
	ds_read_b128 v[208:211], v4 offset:43520
	s_waitcnt lgkmcnt(7)
	v_mfma_f32_16x16x32_bf16 v[172:175], v[212:215], v[80:83], 0
	ds_read_b128 v[212:215], v4 offset:47872
	s_waitcnt lgkmcnt(7)
	v_mfma_f32_16x16x32_bf16 v[176:179], v[224:227], v[80:83], 0
	ds_read_b128 v[224:227], v4 offset:52416
	s_waitcnt lgkmcnt(7)
	v_mfma_f32_16x16x32_bf16 v[180:183], v[228:231], v[80:83], 0
	ds_read_b128 v[228:231], v4 offset:56768
	s_waitcnt lgkmcnt(7)
	v_mfma_f32_16x16x32_bf16 v[184:187], v[232:235], v[80:83], 0
	ds_read_b128 v[232:235], v4 offset:61056
	s_waitcnt lgkmcnt(7)
	v_mfma_f32_16x16x32_bf16 v[188:191], v[236:239], v[80:83], 0
	ds_read_b128 v[236:239], v4 offset:65408
	s_waitcnt lgkmcnt(7)
	v_mfma_f32_16x16x32_bf16 v[160:163], v[200:203], v[84:87], v[160:163]
	ds_read_b128 v[200:203], v4 offset:34944
	s_waitcnt lgkmcnt(7)
	v_mfma_f32_16x16x32_bf16 v[164:167], v[204:207], v[84:87], v[164:167]
	ds_read_b128 v[204:207], v4 offset:39296
	s_waitcnt lgkmcnt(7)
	v_mfma_f32_16x16x32_bf16 v[168:171], v[208:211], v[84:87], v[168:171]
	ds_read_b128 v[208:211], v4 offset:43712
	s_waitcnt lgkmcnt(7)
	v_mfma_f32_16x16x32_bf16 v[172:175], v[212:215], v[84:87], v[172:175]
	ds_read_b128 v[212:215], v4 offset:48064
	s_waitcnt lgkmcnt(7)
	v_mfma_f32_16x16x32_bf16 v[176:179], v[224:227], v[84:87], v[176:179]
	ds_read_b128 v[224:227], v4 offset:52224
	s_waitcnt lgkmcnt(7)
	v_mfma_f32_16x16x32_bf16 v[180:183], v[228:231], v[84:87], v[180:183]
	ds_read_b128 v[228:231], v4 offset:56576
	s_waitcnt lgkmcnt(7)
	v_mfma_f32_16x16x32_bf16 v[184:187], v[232:235], v[84:87], v[184:187]
	ds_read_b128 v[232:235], v4 offset:60992
	s_waitcnt lgkmcnt(7)
	v_mfma_f32_16x16x32_bf16 v[188:191], v[236:239], v[84:87], v[188:191]
	ds_read_b128 v[236:239], v4 offset:65344
	s_waitcnt lgkmcnt(7)
	v_mfma_f32_16x16x32_bf16 v[160:163], v[200:203], v[88:91], v[160:163]
	ds_read_b128 v[200:203], v4 offset:35008
	s_waitcnt lgkmcnt(7)
	v_mfma_f32_16x16x32_bf16 v[164:167], v[204:207], v[88:91], v[164:167]
	ds_read_b128 v[204:207], v4 offset:39360
	s_waitcnt lgkmcnt(7)
	v_mfma_f32_16x16x32_bf16 v[168:171], v[208:211], v[88:91], v[168:171]
	ds_read_b128 v[208:211], v4 offset:43648
	s_waitcnt lgkmcnt(7)
; #define LAS __attribute__((address_space(3)))
; __device__ __forceinline__ unsigned pk2(float lo, float hi) { return pg8::cvt_pk_bf16(lo, hi); }
; __device__ __forceinline__ void gmlp_unit(LAS unsigned char* lds, bf16_t* Z, const float* ln_g, const float* ln_b, const float* b_s, const u32x2 (&uu)[8], const f32x4 (&wreg)[8], const u32x4 (&raw)[4], int cidx, int g, int tid) {
;     ...
;     for (int ks = 0; ks < 4; ++ks) {
;         const bf16x8 bw = *(const LAS bf16x8*)(WS + (wv * 16 + fr) * LSTR + (ks * 32 + fq * 8) * 2);
; #pragma unroll
;         for (int ct = 0; ct < 8; ++ct) { const bf16x8 av = *(const LAS bf16x8*)(VT + (ct * 16 + fr) * LSTR + (ks * 32 + fq * 8) * 2);
;             acc[ct] = __builtin_amdgcn_mfma_f32_16x16x32_bf16(av, bw, acc[ct], 0, 0, 0); }
;     }
;     {
;         const int i = wv * 16 + fr; const float bs = b_s[g * 128 + i];
;         bf16_t* up = Z + (size_t)(row0 + i) * INW + g * 128 + 4 * fq;
; #pragma unroll
;         for (int ct = 0; ct < 8; ++ct) {
;             u32x2 w; w.x = pk2(bf_lo(uu[ct].x) * (acc[ct][0] + bs), bf_hi(uu[ct].x) * (acc[ct][1] + bs)); w.y = pk2(bf_lo(uu[ct].y) * (acc[ct][2] + bs), bf_hi(uu[ct].y) * (acc[ct][3] + bs));
;             *(u32x2*)(up + 16 * ct) = w; }
;     }
;     __syncthreads();
	v_mfma_f32_16x16x32_bf16 v[172:175], v[212:215], v[88:91], v[172:175]
	ds_read_b128 v[212:215], v4 offset:48000
	s_waitcnt lgkmcnt(7)
	v_mfma_f32_16x16x32_bf16 v[176:179], v[224:227], v[88:91], v[176:179]
	ds_read_b128 v[224:227], v4 offset:52288
	s_waitcnt lgkmcnt(7)
	v_mfma_f32_16x16x32_bf16 v[180:183], v[228:231], v[88:91], v[180:183]
	ds_read_b128 v[228:231], v4 offset:56640
	s_waitcnt lgkmcnt(7)
	v_mfma_f32_16x16x32_bf16 v[184:187], v[232:235], v[88:91], v[184:187]
	ds_read_b128 v[232:235], v4 offset:60928
	s_waitcnt lgkmcnt(7)
	v_mfma_f32_16x16x32_bf16 v[188:191], v[236:239], v[88:91], v[188:191]
	ds_read_b128 v[236:239], v4 offset:65280
	s_waitcnt lgkmcnt(7)
	v_mfma_f32_16x16x32_bf16 v[160:163], v[200:203], v[92:95], v[160:163]
	s_waitcnt lgkmcnt(6)
	v_mfma_f32_16x16x32_bf16 v[164:167], v[204:207], v[92:95], v[164:167]
	s_waitcnt lgkmcnt(5)
	v_mfma_f32_16x16x32_bf16 v[168:171], v[208:211], v[92:95], v[168:171]
	s_waitcnt lgkmcnt(4)
	v_mfma_f32_16x16x32_bf16 v[172:175], v[212:215], v[92:95], v[172:175]
	s_waitcnt lgkmcnt(3)
	v_mfma_f32_16x16x32_bf16 v[176:179], v[224:227], v[92:95], v[176:179]
	s_waitcnt lgkmcnt(2)
	v_mfma_f32_16x16x32_bf16 v[180:183], v[228:231], v[92:95], v[180:183]
	s_waitcnt lgkmcnt(1)
	v_mfma_f32_16x16x32_bf16 v[184:187], v[232:235], v[92:95], v[184:187]
	s_waitcnt lgkmcnt(0)
	v_mfma_f32_16x16x32_bf16 v[188:191], v[236:239], v[92:95], v[188:191]
	s_waitcnt vmcnt(8)
	v_add_f32_e32 v160, v160, v7
	v_add_f32_e32 v161, v161, v7
	v_add_f32_e32 v162, v162, v7
	v_add_f32_e32 v163, v163, v7
	v_lshlrev_b32_e32 v8, 16, v144
	v_and_b32_e32 v9, 0xffff0000, v144
	v_lshlrev_b32_e32 v10, 16, v145
	v_and_b32_e32 v11, 0xffff0000, v145
	v_mul_f32_e32 v160, v8, v160
	v_mul_f32_e32 v161, v9, v161
	v_mul_f32_e32 v162, v10, v162
	v_mul_f32_e32 v163, v11, v163
	v_cvt_pk_bf16_f32 v12, v160, v161
	v_cvt_pk_bf16_f32 v13, v162, v163
	global_store_dwordx2 v2, v[12:13], s[28:29]
	s_nop 0
	v_add_f32_e32 v164, v164, v7
	v_add_f32_e32 v165, v165, v7
	v_add_f32_e32 v166, v166, v7
	v_add_f32_e32 v167, v167, v7
	v_lshlrev_b32_e32 v8, 16, v146
	v_and_b32_e32 v9, 0xffff0000, v146
	v_lshlrev_b32_e32 v10, 16, v147
	v_and_b32_e32 v11, 0xffff0000, v147
	v_mul_f32_e32 v164, v8, v164
	v_mul_f32_e32 v165, v9, v165
	v_mul_f32_e32 v166, v10, v166
	v_mul_f32_e32 v167, v11, v167
	v_cvt_pk_bf16_f32 v12, v164, v165
	v_cvt_pk_bf16_f32 v13, v166, v167
	global_store_dwordx2 v2, v[12:13], s[28:29] offset:32
	s_nop 0
	v_add_f32_e32 v168, v168, v7
	v_add_f32_e32 v169, v169, v7
	v_add_f32_e32 v170, v170, v7
	v_add_f32_e32 v171, v171, v7
	v_lshlrev_b32_e32 v8, 16, v148
	v_and_b32_e32 v9, 0xffff0000, v148
	v_lshlrev_b32_e32 v10, 16, v149
	v_and_b32_e32 v11, 0xffff0000, v149
	v_mul_f32_e32 v168, v8, v168
	v_mul_f32_e32 v169, v9, v169
	v_mul_f32_e32 v170, v10, v170
	v_mul_f32_e32 v171, v11, v171
	v_cvt_pk_bf16_f32 v12, v168, v169
	v_cvt_pk_bf16_f32 v13, v170, v171
	global_store_dwordx2 v2, v[12:13], s[28:29] offset:64
	s_nop 0
	v_add_f32_e32 v172, v172, v7
	v_add_f32_e32 v173, v173, v7
	v_add_f32_e32 v174, v174, v7
	v_add_f32_e32 v175, v175, v7
	v_lshlrev_b32_e32 v8, 16, v150
	v_and_b32_e32 v9, 0xffff0000, v150
	v_lshlrev_b32_e32 v10, 16, v151
	v_and_b32_e32 v11, 0xffff0000, v151
	v_mul_f32_e32 v172, v8, v172
	v_mul_f32_e32 v173, v9, v173
	v_mul_f32_e32 v174, v10, v174
	v_mul_f32_e32 v175, v11, v175
	v_cvt_pk_bf16_f32 v12, v172, v173
	v_cvt_pk_bf16_f32 v13, v174, v175
	global_store_dwordx2 v2, v[12:13], s[28:29] offset:96
	s_nop 0
	v_add_f32_e32 v176, v176, v7
	v_add_f32_e32 v177, v177, v7
	v_add_f32_e32 v178, v178, v7
	v_add_f32_e32 v179, v179, v7
	v_lshlrev_b32_e32 v8, 16, v152
	v_and_b32_e32 v9, 0xffff0000, v152
	v_lshlrev_b32_e32 v10, 16, v153
	v_and_b32_e32 v11, 0xffff0000, v153
	v_mul_f32_e32 v176, v8, v176
	v_mul_f32_e32 v177, v9, v177
	v_mul_f32_e32 v178, v10, v178
	v_mul_f32_e32 v179, v11, v179
	v_cvt_pk_bf16_f32 v12, v176, v177
	v_cvt_pk_bf16_f32 v13, v178, v179
	global_store_dwordx2 v2, v[12:13], s[28:29] offset:128
	s_nop 0
	v_add_f32_e32 v180, v180, v7
	v_add_f32_e32 v181, v181, v7
	v_add_f32_e32 v182, v182, v7
	v_add_f32_e32 v183, v183, v7
	v_lshlrev_b32_e32 v8, 16, v154
	v_and_b32_e32 v9, 0xffff0000, v154
	v_lshlrev_b32_e32 v10, 16, v155
	v_and_b32_e32 v11, 0xffff0000, v155
	v_mul_f32_e32 v180, v8, v180
	v_mul_f32_e32 v181, v9, v181
	v_mul_f32_e32 v182, v10, v182
	v_mul_f32_e32 v183, v11, v183
	v_cvt_pk_bf16_f32 v12, v180, v181
	v_cvt_pk_bf16_f32 v13, v182, v183
	global_store_dwordx2 v2, v[12:13], s[28:29] offset:160
	s_nop 0
	v_add_f32_e32 v184, v184, v7
	v_add_f32_e32 v185, v185, v7
	v_add_f32_e32 v186, v186, v7
	v_add_f32_e32 v187, v187, v7
	v_lshlrev_b32_e32 v8, 16, v156
	v_and_b32_e32 v9, 0xffff0000, v156
	v_lshlrev_b32_e32 v10, 16, v157
	v_and_b32_e32 v11, 0xffff0000, v157
	v_mul_f32_e32 v184, v8, v184
	v_mul_f32_e32 v185, v9, v185
	v_mul_f32_e32 v186, v10, v186
	v_mul_f32_e32 v187, v11, v187
	v_cvt_pk_bf16_f32 v12, v184, v185
	v_cvt_pk_bf16_f32 v13, v186, v187
	global_store_dwordx2 v2, v[12:13], s[28:29] offset:192
	s_nop 0
	v_add_f32_e32 v188, v188, v7
	v_add_f32_e32 v189, v189, v7
	v_add_f32_e32 v190, v190, v7
	v_add_f32_e32 v191, v191, v7
	v_lshlrev_b32_e32 v8, 16, v158
	v_and_b32_e32 v9, 0xffff0000, v158
	v_lshlrev_b32_e32 v10, 16, v159
	v_and_b32_e32 v11, 0xffff0000, v159
	v_mul_f32_e32 v188, v8, v188
	v_mul_f32_e32 v189, v9, v189
	v_mul_f32_e32 v190, v10, v190
	v_mul_f32_e32 v191, v11, v191
	v_cvt_pk_bf16_f32 v12, v188, v189
	v_cvt_pk_bf16_f32 v13, v190, v191
	global_store_dwordx2 v2, v[12:13], s[28:29] offset:224
	s_barrier
